# GEMM K-loops: per-cluster s_setprio flips replaced by one static priority raise for the trailing wave half
# speedup vs baseline: 1.0136x; 1.0136x over previous
; #define PG8_STAGE(bufoff, gbase, voff) do { _Pragma("unroll") for (int _i = 0; _i < 2; ++_i) \
;         __builtin_amdgcn_global_load_lds((const unsigned*)((const char*)(gbase) + (voff)[_i]), (PG8_LAS unsigned*)(lds + (bufoff) + ldsw + _i * 8192), 16, 0, 0); } while (0)
; #define PG8_LDA(dst, b, h) do { _Pragma("unroll") for (int m = 0; m < 4; ++m) _Pragma("unroll") for (int k = 0; k < 2; ++k) dst[m][k] = *(const PG8_LAS bf16x8*)(lds + PG8_SA(b, h) + aoff + m * 2048 + k * 1024); } while (0)
; #define PG8_LDB(dst, b, h) do { _Pragma("unroll") for (int n = 0; n < 2; ++n) _Pragma("unroll") for (int k = 0; k < 2; ++k) dst[n][k] = *(const PG8_LAS bf16x8*)(lds + PG8_SB(b, h) + boff + n * 2048 + k * 1024); } while (0)
; #define PG8_WAIT_V(n) asm volatile("s_waitcnt vmcnt(" #n ")" ::: "memory")
; #define PG8_WAIT_L(n) asm volatile("s_waitcnt lgkmcnt(" #n ")" ::: "memory")
; template <class Epi, class Sched, bool ALIGN_EPI = false, bool SP2 = false>
; __device__ __forceinline__ void gemm_phase(PG8_LAS unsigned char* lds, const Gemm g, const Sched& S, const Epi& E) {
;     ...
;         const bool has_next = S.next(ui + 1, nxt);
;         const char* nA = has_next ? (const char*)g.A + (size_t)nxt.pm * tstep : cA; const char* nB = has_next ? (const char*)g.Bt + (size_t)nxt.pn * tstep : cB;
;         asm volatile(".p2align 6" ::: "memory");
;         for (int t = 0; t < nt; t += 2) {
;             const bool last = (t == nt - 2);
;             const char* a1 = cA + (size_t)(t + 1) * kstep;
;             const char* a2 = last ? nA : cA + (size_t)(t + 2) * kstep; const char* b2 = last ? nB : cB + (size_t)(t + 2) * kstep;
;             const char* a3 = a2 + kstep; const char* b3 = b2 + kstep;
;             if (last && has_next) S.a_ready(nxt);
;             if constexpr (SP2) {
;             PG8_LDB(B0, 0, 0); PG8_LDB(B1, 0, 1); PG8_SCHED; PG8_LDA(At, 0, 0); PG8_STAGE(PG8_SA(1, 1), a1 + hstep, voffA);
;             PG8_WAIT_V(8); PG8_WAIT_L(0); PG8_BAR; PG8_MMA(0, 0, At, B0); PG8_MMA(0, 1, At, B1); PG8_BAR; PG8_SCHED;
;     ...
; #pragma unroll
;         for (int a = 0; a < 2; ++a)
; #pragma unroll
;             for (int b = 0; b < 2; ++b)
; #pragma unroll
;                 for (int m = 0; m < 4; ++m)
; #pragma unroll
;                     for (int n = 0; n < 2; ++n) acc[a][b][m][n] = (f32x4){0.f, 0.f, 0.f, 0.f};
;         cur = nxt; cA = nA; cB = nB; ++ui;
.LBB0_386:
	s_ashr_i32 s77, s76, 31
	s_lshl_b64 s[44:45], s[76:77], 19
	s_add_u32 s78, s26, s44
	s_addc_u32 s79, s27, s45
	s_and_b64 s[44:45], s[4:5], exec
	s_cselect_b32 s2, s79, s83
	s_cselect_b32 s7, s78, s82
	s_ashr_i32 s75, s74, 31
	s_lshl_b64 s[44:45], s[74:75], 19
	s_add_u32 s80, s50, s44
	s_addc_u32 s81, s51, s45
	s_and_b64 s[44:45], s[4:5], exec
	s_cselect_b32 s12, s81, s85
	s_cselect_b32 s17, s80, s84
	s_add_u32 s82, s82, 0x40080
	.p2align 6
	s_addc_u32 s83, s83, 0
	s_add_u32 s44, s84, 0x100
	v_mov_b32_e32 v0, 0
	s_addc_u32 s45, s85, 0
	s_mov_b32 s75, -2
	v_mov_b32_e32 v1, v0
	s_waitcnt lgkmcnt(0)
	v_mov_b32_e32 v2, v0
	v_mov_b32_e32 v3, v0
	v_mov_b32_e32 v8, v0
	v_mov_b32_e32 v9, v0
	v_mov_b32_e32 v10, v0
	v_mov_b32_e32 v11, v0
	v_mov_b32_e32 v16, v0
	v_mov_b32_e32 v17, v0
	v_mov_b32_e32 v18, v0
	v_mov_b32_e32 v19, v0
	v_mov_b32_e32 v24, v0
	v_mov_b32_e32 v25, v0
	v_mov_b32_e32 v26, v0
	v_mov_b32_e32 v27, v0
	v_mov_b32_e32 v32, v0
	v_mov_b32_e32 v33, v0
	v_mov_b32_e32 v34, v0
	v_mov_b32_e32 v35, v0
	v_mov_b32_e32 v40, v0
	v_mov_b32_e32 v41, v0
	v_mov_b32_e32 v42, v0
	v_mov_b32_e32 v43, v0
	v_mov_b32_e32 v48, v0
	v_mov_b32_e32 v49, v0
	v_mov_b32_e32 v50, v0
	v_mov_b32_e32 v51, v0
	v_mov_b32_e32 v56, v0
	v_mov_b32_e32 v57, v0
	v_mov_b32_e32 v58, v0
	v_mov_b32_e32 v59, v0
	v_mov_b32_e32 v4, v0
	v_mov_b32_e32 v5, v0
	v_mov_b32_e32 v6, v0
	v_mov_b32_e32 v7, v0
	v_mov_b32_e32 v12, v0
	v_mov_b32_e32 v13, v0
	v_mov_b32_e32 v14, v0
	v_mov_b32_e32 v15, v0
	v_mov_b32_e32 v20, v0
	v_mov_b32_e32 v21, v0
	v_mov_b32_e32 v22, v0
	v_mov_b32_e32 v23, v0
	v_mov_b32_e32 v28, v0
	v_mov_b32_e32 v29, v0
	v_mov_b32_e32 v30, v0
	v_mov_b32_e32 v31, v0
	v_mov_b32_e32 v36, v0
	v_mov_b32_e32 v37, v0
	v_mov_b32_e32 v38, v0
	v_mov_b32_e32 v39, v0
	v_mov_b32_e32 v44, v0
	v_mov_b32_e32 v45, v0
	v_mov_b32_e32 v46, v0
	v_mov_b32_e32 v47, v0
	v_mov_b32_e32 v52, v0
	v_mov_b32_e32 v53, v0
	v_mov_b32_e32 v54, v0
	v_mov_b32_e32 v55, v0
	v_mov_b32_e32 v60, v0
	v_mov_b32_e32 v61, v0
	v_mov_b32_e32 v62, v0
	v_mov_b32_e32 v63, v0
	v_mov_b32_e32 v64, v0
	v_mov_b32_e32 v65, v0
	v_mov_b32_e32 v66, v0
	v_mov_b32_e32 v67, v0
	v_mov_b32_e32 v72, v0
	v_mov_b32_e32 v73, v0
	v_mov_b32_e32 v74, v0
	v_mov_b32_e32 v75, v0
	v_mov_b32_e32 v80, v0
	v_mov_b32_e32 v81, v0
	v_mov_b32_e32 v82, v0
	v_mov_b32_e32 v83, v0
	v_mov_b32_e32 v88, v0
	v_mov_b32_e32 v89, v0
	v_mov_b32_e32 v90, v0
	v_mov_b32_e32 v91, v0
	v_mov_b32_e32 v96, v0
	v_mov_b32_e32 v97, v0
	v_mov_b32_e32 v98, v0
	v_mov_b32_e32 v99, v0
	v_mov_b32_e32 v104, v0
	v_mov_b32_e32 v105, v0
	v_mov_b32_e32 v106, v0
	v_mov_b32_e32 v107, v0
	v_mov_b32_e32 v112, v0
	v_mov_b32_e32 v113, v0
	v_mov_b32_e32 v114, v0
	v_mov_b32_e32 v115, v0
	v_mov_b32_e32 v120, v0
	v_mov_b32_e32 v121, v0
	v_mov_b32_e32 v122, v0
	v_mov_b32_e32 v123, v0
	v_mov_b32_e32 v68, v0
	v_mov_b32_e32 v69, v0
	v_mov_b32_e32 v70, v0
	v_mov_b32_e32 v71, v0
	v_mov_b32_e32 v76, v0
	v_mov_b32_e32 v77, v0
	v_mov_b32_e32 v78, v0
	v_mov_b32_e32 v79, v0
	v_mov_b32_e32 v84, v0
	v_mov_b32_e32 v85, v0
	v_mov_b32_e32 v86, v0
	v_mov_b32_e32 v87, v0
	v_mov_b32_e32 v92, v0
	v_mov_b32_e32 v93, v0
	v_mov_b32_e32 v94, v0
	v_mov_b32_e32 v95, v0
	v_mov_b32_e32 v100, v0
	v_mov_b32_e32 v101, v0
	v_mov_b32_e32 v102, v0
	v_mov_b32_e32 v103, v0
	v_mov_b32_e32 v108, v0
	v_mov_b32_e32 v109, v0
	v_mov_b32_e32 v110, v0
	v_mov_b32_e32 v111, v0
	v_mov_b32_e32 v116, v0
	v_mov_b32_e32 v117, v0
	v_mov_b32_e32 v118, v0
	v_mov_b32_e32 v119, v0
	v_mov_b32_e32 v124, v0
	v_mov_b32_e32 v125, v0
	v_mov_b32_e32 v126, v0
	v_mov_b32_e32 v127, v0
	s_cmp_eq_u64 s[56:57], 0
	s_cbranch_scc0 .Lprio_387
	s_setprio 1
.Lprio_387:
.LBB0_387:
	ds_read_b128 v[128:131], v171
	ds_read_b128 v[132:135], v171 offset:1024
	ds_read_b128 v[136:139], v171 offset:2048
	ds_read_b128 v[182:185], v171 offset:3072
	ds_read_b128 v[186:189], v173
	ds_read_b128 v[190:193], v173 offset:1024
	ds_read_b128 v[194:197], v173 offset:2048
	ds_read_b128 v[198:201], v173 offset:3072
	s_add_u32 s77, s82, 0xfffc0080
	s_addc_u32 s84, s83, -1
	s_cmp_eq_u32 s75, 12
	s_cselect_b32 s87, s2, s84
	s_cselect_b32 s86, s7, s77
	s_cselect_b32 s85, s12, s45
	s_cselect_b32 s84, s17, s44
	v_lshl_add_u64 v[168:169], s[82:83], 0, v[158:159]
	s_add_i32 m0, s11, 0xc000
	ds_read_b128 v[202:205], v175
	ds_read_b128 v[206:209], v175 offset:1024
	ds_read_b128 v[210:213], v175 offset:2048
	ds_read_b128 v[214:217], v175 offset:3072
	ds_read_b128 v[218:221], v175 offset:4096
	ds_read_b128 v[226:229], v175 offset:5120
	ds_read_b128 v[230:233], v175 offset:6144
	ds_read_b128 v[236:239], v175 offset:7168
	global_load_lds_dwordx4 v[168:169], off
	v_lshl_add_u64 v[168:169], s[82:83], 0, v[160:161]
	s_add_i32 m0, s11, 0xe000
	s_nop 0
	global_load_lds_dwordx4 v[168:169], off
	s_waitcnt vmcnt(8)
	s_waitcnt lgkmcnt(0)
	s_barrier
; #define PG8_STAGE(bufoff, gbase, voff) do { _Pragma("unroll") for (int _i = 0; _i < 2; ++_i) \
;         __builtin_amdgcn_global_load_lds((const unsigned*)((const char*)(gbase) + (voff)[_i]), (PG8_LAS unsigned*)(lds + (bufoff) + ldsw + _i * 8192), 16, 0, 0); } while (0)
; #define PG8_LDA(dst, b, h) do { _Pragma("unroll") for (int m = 0; m < 4; ++m) _Pragma("unroll") for (int k = 0; k < 2; ++k) dst[m][k] = *(const PG8_LAS bf16x8*)(lds + PG8_SA(b, h) + aoff + m * 2048 + k * 1024); } while (0)
; #define PG8_LDB(dst, b, h) do { _Pragma("unroll") for (int n = 0; n < 2; ++n) _Pragma("unroll") for (int k = 0; k < 2; ++k) dst[n][k] = *(const PG8_LAS bf16x8*)(lds + PG8_SB(b, h) + boff + n * 2048 + k * 1024); } while (0)
; #define PG8_MMA(ai, bj, At, Bt) do { __builtin_amdgcn_s_setprio(1); _Pragma("unroll") for (int m = 0; m < 4; ++m) _Pragma("unroll") for (int n = 0; n < 2; ++n) _Pragma("unroll") for (int k = 0; k < 2; ++k) \
;         acc[ai][bj][m][n] = __builtin_amdgcn_mfma_f32_16x16x32_bf16(Bt[n][k], At[m][k], acc[ai][bj][m][n], 0, 0, 0); __builtin_amdgcn_s_setprio(0); } while (0)
; #define PG8_WAIT_V(n) asm volatile("s_waitcnt vmcnt(" #n ")" ::: "memory")
; #define PG8_WAIT_L(n) asm volatile("s_waitcnt lgkmcnt(" #n ")" ::: "memory")
; #define PG8_BAR __builtin_amdgcn_s_barrier()
; #define PG8_SCHED __builtin_amdgcn_sched_barrier(0)
; template <class Epi, class Sched, bool ALIGN_EPI = false, bool SP2 = false>
; __device__ __forceinline__ void gemm_phase(PG8_LAS unsigned char* lds, const Gemm g, const Sched& S, const Epi& E) {
;     ...
;             PG8_WAIT_V(8); PG8_WAIT_L(0); PG8_BAR; PG8_MMA(0, 0, At, B0); PG8_MMA(0, 1, At, B1); PG8_BAR; PG8_SCHED;
;             PG8_LDA(At, 0, 1); PG8_STAGE(PG8_SB(0, 0), b2, voffB); PG8_STAGE(PG8_SB(0, 1), b2 + hstep, voffB); PG8_STAGE(PG8_SA(0, 0), a2, voffA);
;             PG8_WAIT_V(8); PG8_WAIT_L(0); PG8_BAR; PG8_MMA(1, 0, At, B0); PG8_MMA(1, 1, At, B1); PG8_BAR; PG8_SCHED;
;             PG8_LDB(B0, 1, 0); PG8_LDB(B1, 1, 1); PG8_SCHED; PG8_LDA(At, 1, 0); PG8_STAGE(PG8_SA(0, 1), a2 + hstep, voffA);
;             PG8_WAIT_V(8); PG8_WAIT_L(0); PG8_BAR; PG8_MMA(0, 0, At, B0); PG8_MMA(0, 1, At, B1); PG8_BAR; PG8_SCHED;
	s_waitcnt lgkmcnt(0)
	v_mfma_f32_16x16x32_bf16 v[124:127], v[128:131], v[202:205], v[124:127]
	v_mfma_f32_16x16x32_bf16 v[116:119], v[136:139], v[202:205], v[116:119]
	v_mfma_f32_16x16x32_bf16 v[108:111], v[128:131], v[210:213], v[108:111]
	v_mfma_f32_16x16x32_bf16 v[100:103], v[136:139], v[210:213], v[100:103]
	v_mfma_f32_16x16x32_bf16 v[92:95], v[128:131], v[218:221], v[92:95]
	v_mfma_f32_16x16x32_bf16 v[84:87], v[136:139], v[218:221], v[84:87]
	v_mfma_f32_16x16x32_bf16 v[76:79], v[128:131], v[230:233], v[76:79]
	v_mfma_f32_16x16x32_bf16 v[68:71], v[136:139], v[230:233], v[68:71]
	v_mfma_f32_16x16x32_bf16 v[124:127], v[132:135], v[206:209], v[124:127]
	v_mfma_f32_16x16x32_bf16 v[116:119], v[182:185], v[206:209], v[116:119]
	v_mfma_f32_16x16x32_bf16 v[108:111], v[132:135], v[214:217], v[108:111]
	v_mfma_f32_16x16x32_bf16 v[100:103], v[182:185], v[214:217], v[100:103]
	v_mfma_f32_16x16x32_bf16 v[92:95], v[132:135], v[226:229], v[92:95]
	v_mfma_f32_16x16x32_bf16 v[84:87], v[182:185], v[226:229], v[84:87]
	v_mfma_f32_16x16x32_bf16 v[76:79], v[132:135], v[236:239], v[76:79]
	v_mfma_f32_16x16x32_bf16 v[68:71], v[182:185], v[236:239], v[68:71]
	v_mfma_f32_16x16x32_bf16 v[120:123], v[186:189], v[202:205], v[120:123]
	v_mfma_f32_16x16x32_bf16 v[112:115], v[194:197], v[202:205], v[112:115]
	v_mfma_f32_16x16x32_bf16 v[104:107], v[186:189], v[210:213], v[104:107]
	v_mfma_f32_16x16x32_bf16 v[96:99], v[194:197], v[210:213], v[96:99]
	v_mfma_f32_16x16x32_bf16 v[88:91], v[186:189], v[218:221], v[88:91]
	v_mfma_f32_16x16x32_bf16 v[80:83], v[194:197], v[218:221], v[80:83]
	v_mfma_f32_16x16x32_bf16 v[72:75], v[186:189], v[230:233], v[72:75]
	v_mfma_f32_16x16x32_bf16 v[64:67], v[194:197], v[230:233], v[64:67]
	v_mfma_f32_16x16x32_bf16 v[120:123], v[190:193], v[206:209], v[120:123]
	v_mfma_f32_16x16x32_bf16 v[112:115], v[198:201], v[206:209], v[112:115]
	v_mfma_f32_16x16x32_bf16 v[104:107], v[190:193], v[214:217], v[104:107]
	v_mfma_f32_16x16x32_bf16 v[96:99], v[198:201], v[214:217], v[96:99]
	v_mfma_f32_16x16x32_bf16 v[88:91], v[190:193], v[226:229], v[88:91]
	v_mfma_f32_16x16x32_bf16 v[80:83], v[198:201], v[226:229], v[80:83]
	v_mfma_f32_16x16x32_bf16 v[72:75], v[190:193], v[236:239], v[72:75]
	v_mfma_f32_16x16x32_bf16 v[64:67], v[198:201], v[236:239], v[64:67]
	s_barrier
	s_add_i32 s77, s31, s71
	v_lshl_add_u64 v[168:169], s[84:85], 0, v[142:143]
	s_mov_b32 m0, s77
	ds_read_b128 v[202:205], v175 offset:16384
	ds_read_b128 v[206:209], v175 offset:17408
	ds_read_b128 v[210:213], v175 offset:18432
	ds_read_b128 v[214:217], v175 offset:19456
	ds_read_b128 v[218:221], v175 offset:20480
	ds_read_b128 v[226:229], v175 offset:21504
	ds_read_b128 v[230:233], v175 offset:22528
	ds_read_b128 v[236:239], v175 offset:23552
	global_load_lds_dwordx4 v[168:169], off
	s_add_i32 m0, s77, 0x2000
	s_add_u32 s90, s84, 0x40000
	v_lshl_add_u64 v[178:179], s[84:85], 0, v[146:147]
	s_addc_u32 s91, s85, 0
	s_add_i32 s77, s22, s71
	global_load_lds_dwordx4 v[178:179], off
	v_lshl_add_u64 v[222:223], s[90:91], 0, v[142:143]
	s_mov_b32 m0, s77
	v_lshl_add_u64 v[240:241], s[86:87], 0, v[144:145]
	global_load_lds_dwordx4 v[222:223], off
	v_lshl_add_u64 v[244:245], s[90:91], 0, v[146:147]
	v_lshl_add_u64 v[222:223], s[86:87], 0, v[140:141]
	s_waitcnt vmcnt(5)
	s_waitcnt lgkmcnt(0)
	s_barrier
	s_waitcnt lgkmcnt(0)
	v_mfma_f32_16x16x32_bf16 v[60:63], v[128:131], v[202:205], v[60:63]
	v_mfma_f32_16x16x32_bf16 v[52:55], v[136:139], v[202:205], v[52:55]
	v_mfma_f32_16x16x32_bf16 v[44:47], v[128:131], v[210:213], v[44:47]
	v_mfma_f32_16x16x32_bf16 v[36:39], v[136:139], v[210:213], v[36:39]
	s_add_i32 m0, s77, 0x2000
	v_mfma_f32_16x16x32_bf16 v[28:31], v[128:131], v[218:221], v[28:31]
	global_load_lds_dwordx4 v[244:245], off
	v_mfma_f32_16x16x32_bf16 v[20:23], v[136:139], v[218:221], v[20:23]
	v_mfma_f32_16x16x32_bf16 v[12:15], v[128:131], v[230:233], v[12:15]
	v_mfma_f32_16x16x32_bf16 v[4:7], v[136:139], v[230:233], v[4:7]
	v_mfma_f32_16x16x32_bf16 v[60:63], v[132:135], v[206:209], v[60:63]
	v_mfma_f32_16x16x32_bf16 v[52:55], v[182:185], v[206:209], v[52:55]
	v_mfma_f32_16x16x32_bf16 v[44:47], v[132:135], v[214:217], v[44:47]
	v_mfma_f32_16x16x32_bf16 v[36:39], v[182:185], v[214:217], v[36:39]
	s_mov_b32 m0, s11
	v_mfma_f32_16x16x32_bf16 v[28:31], v[132:135], v[226:229], v[28:31]
	global_load_lds_dwordx4 v[222:223], off
	v_mfma_f32_16x16x32_bf16 v[20:23], v[182:185], v[226:229], v[20:23]
	v_mfma_f32_16x16x32_bf16 v[12:15], v[132:135], v[236:239], v[12:15]
	v_mfma_f32_16x16x32_bf16 v[4:7], v[182:185], v[236:239], v[4:7]
	v_mfma_f32_16x16x32_bf16 v[56:59], v[186:189], v[202:205], v[56:59]
	v_mfma_f32_16x16x32_bf16 v[48:51], v[194:197], v[202:205], v[48:51]
	v_mfma_f32_16x16x32_bf16 v[40:43], v[186:189], v[210:213], v[40:43]
	v_mfma_f32_16x16x32_bf16 v[32:35], v[194:197], v[210:213], v[32:35]
	s_mov_b32 m0, s89
	v_mfma_f32_16x16x32_bf16 v[24:27], v[186:189], v[218:221], v[24:27]
	global_load_lds_dwordx4 v[240:241], off
	v_mfma_f32_16x16x32_bf16 v[16:19], v[194:197], v[218:221], v[16:19]
	v_mfma_f32_16x16x32_bf16 v[8:11], v[186:189], v[230:233], v[8:11]
	v_mfma_f32_16x16x32_bf16 v[0:3], v[194:197], v[230:233], v[0:3]
	v_mfma_f32_16x16x32_bf16 v[56:59], v[190:193], v[206:209], v[56:59]
	v_mfma_f32_16x16x32_bf16 v[48:51], v[198:201], v[206:209], v[48:51]
	v_mfma_f32_16x16x32_bf16 v[40:43], v[190:193], v[214:217], v[40:43]
	v_mfma_f32_16x16x32_bf16 v[32:35], v[198:201], v[214:217], v[32:35]
	v_mfma_f32_16x16x32_bf16 v[24:27], v[190:193], v[226:229], v[24:27]
	v_mfma_f32_16x16x32_bf16 v[16:19], v[198:201], v[226:229], v[16:19]
	v_mfma_f32_16x16x32_bf16 v[8:11], v[190:193], v[236:239], v[8:11]
	v_mfma_f32_16x16x32_bf16 v[0:3], v[198:201], v[236:239], v[0:3]
	s_barrier
; #define PG8_STAGE(bufoff, gbase, voff) do { _Pragma("unroll") for (int _i = 0; _i < 2; ++_i) \
;         __builtin_amdgcn_global_load_lds((const unsigned*)((const char*)(gbase) + (voff)[_i]), (PG8_LAS unsigned*)(lds + (bufoff) + ldsw + _i * 8192), 16, 0, 0); } while (0)
; #define PG8_LDA(dst, b, h) do { _Pragma("unroll") for (int m = 0; m < 4; ++m) _Pragma("unroll") for (int k = 0; k < 2; ++k) dst[m][k] = *(const PG8_LAS bf16x8*)(lds + PG8_SA(b, h) + aoff + m * 2048 + k * 1024); } while (0)
; #define PG8_LDB(dst, b, h) do { _Pragma("unroll") for (int n = 0; n < 2; ++n) _Pragma("unroll") for (int k = 0; k < 2; ++k) dst[n][k] = *(const PG8_LAS bf16x8*)(lds + PG8_SB(b, h) + boff + n * 2048 + k * 1024); } while (0)
; #define PG8_MMA(ai, bj, At, Bt) do { __builtin_amdgcn_s_setprio(1); _Pragma("unroll") for (int m = 0; m < 4; ++m) _Pragma("unroll") for (int n = 0; n < 2; ++n) _Pragma("unroll") for (int k = 0; k < 2; ++k) \
;         acc[ai][bj][m][n] = __builtin_amdgcn_mfma_f32_16x16x32_bf16(Bt[n][k], At[m][k], acc[ai][bj][m][n], 0, 0, 0); __builtin_amdgcn_s_setprio(0); } while (0)
; #define PG8_WAIT_V(n) asm volatile("s_waitcnt vmcnt(" #n ")" ::: "memory")
; #define PG8_WAIT_L(n) asm volatile("s_waitcnt lgkmcnt(" #n ")" ::: "memory")
; #define PG8_BAR __builtin_amdgcn_s_barrier()
; #define PG8_SCHED __builtin_amdgcn_sched_barrier(0)
; template <class Epi, class Sched, bool ALIGN_EPI = false, bool SP2 = false>
; __device__ __forceinline__ void gemm_phase(PG8_LAS unsigned char* lds, const Gemm g, const Sched& S, const Epi& E) {
;     ...
;             PG8_LDB(B0, 1, 0); PG8_LDB(B1, 1, 1); PG8_SCHED; PG8_LDA(At, 1, 0); PG8_STAGE(PG8_SA(0, 1), a2 + hstep, voffA);
;             PG8_WAIT_V(8); PG8_WAIT_L(0); PG8_BAR; PG8_MMA(0, 0, At, B0); PG8_MMA(0, 1, At, B1); PG8_BAR; PG8_SCHED;
	s_add_i32 s77, 0, 0x18000
	v_add_u32_e32 v148, s77, v167
	s_add_i32 s88, 0, 0x1c000
	ds_read_b128 v[128:131], v148
	ds_read_b128 v[132:135], v148 offset:1024
	ds_read_b128 v[136:139], v148 offset:2048
	ds_read_b128 v[182:185], v148 offset:3072
	v_add_u32_e32 v148, s88, v167
	ds_read_b128 v[186:189], v148
	ds_read_b128 v[190:193], v148 offset:1024
	ds_read_b128 v[194:197], v148 offset:2048
	ds_read_b128 v[198:201], v148 offset:3072
	s_add_u32 s86, s86, 0x40000
	s_addc_u32 s87, s87, 0
	s_mov_b32 m0, s95
	v_lshl_add_u64 v[242:243], s[86:87], 0, v[140:141]
	ds_read_b128 v[202:205], v175 offset:32768
	ds_read_b128 v[206:209], v175 offset:33792
	ds_read_b128 v[210:213], v175 offset:34816
	ds_read_b128 v[214:217], v175 offset:35840
	ds_read_b128 v[218:221], v175 offset:36864
	ds_read_b128 v[226:229], v175 offset:37888
	ds_read_b128 v[230:233], v175 offset:38912
	ds_read_b128 v[236:239], v175 offset:39936
	global_load_lds_dwordx4 v[242:243], off
	v_lshl_add_u64 v[242:243], s[86:87], 0, v[144:145]
	s_mov_b32 m0, s96
	s_nop 0
	global_load_lds_dwordx4 v[242:243], off
	s_waitcnt vmcnt(8)
	s_waitcnt lgkmcnt(0)
	s_barrier
	s_waitcnt lgkmcnt(0)
	v_mfma_f32_16x16x32_bf16 v[124:127], v[128:131], v[202:205], v[124:127]
	v_mfma_f32_16x16x32_bf16 v[116:119], v[136:139], v[202:205], v[116:119]
	v_mfma_f32_16x16x32_bf16 v[108:111], v[128:131], v[210:213], v[108:111]
	v_mfma_f32_16x16x32_bf16 v[100:103], v[136:139], v[210:213], v[100:103]
	v_mfma_f32_16x16x32_bf16 v[92:95], v[128:131], v[218:221], v[92:95]
	v_mfma_f32_16x16x32_bf16 v[84:87], v[136:139], v[218:221], v[84:87]
	v_mfma_f32_16x16x32_bf16 v[76:79], v[128:131], v[230:233], v[76:79]
	v_mfma_f32_16x16x32_bf16 v[68:71], v[136:139], v[230:233], v[68:71]
	v_mfma_f32_16x16x32_bf16 v[124:127], v[132:135], v[206:209], v[124:127]
	v_mfma_f32_16x16x32_bf16 v[116:119], v[182:185], v[206:209], v[116:119]
	v_mfma_f32_16x16x32_bf16 v[108:111], v[132:135], v[214:217], v[108:111]
	v_mfma_f32_16x16x32_bf16 v[100:103], v[182:185], v[214:217], v[100:103]
	v_mfma_f32_16x16x32_bf16 v[92:95], v[132:135], v[226:229], v[92:95]
	v_mfma_f32_16x16x32_bf16 v[84:87], v[182:185], v[226:229], v[84:87]
	v_mfma_f32_16x16x32_bf16 v[76:79], v[132:135], v[236:239], v[76:79]
	v_mfma_f32_16x16x32_bf16 v[68:71], v[182:185], v[236:239], v[68:71]
	v_mfma_f32_16x16x32_bf16 v[120:123], v[186:189], v[202:205], v[120:123]
	v_mfma_f32_16x16x32_bf16 v[112:115], v[194:197], v[202:205], v[112:115]
	v_mfma_f32_16x16x32_bf16 v[104:107], v[186:189], v[210:213], v[104:107]
	v_mfma_f32_16x16x32_bf16 v[96:99], v[194:197], v[210:213], v[96:99]
	v_mfma_f32_16x16x32_bf16 v[88:91], v[186:189], v[218:221], v[88:91]
	v_mfma_f32_16x16x32_bf16 v[80:83], v[194:197], v[218:221], v[80:83]
	v_mfma_f32_16x16x32_bf16 v[72:75], v[186:189], v[230:233], v[72:75]
	v_mfma_f32_16x16x32_bf16 v[64:67], v[194:197], v[230:233], v[64:67]
	v_mfma_f32_16x16x32_bf16 v[120:123], v[190:193], v[206:209], v[120:123]
	v_mfma_f32_16x16x32_bf16 v[112:115], v[198:201], v[206:209], v[112:115]
	v_mfma_f32_16x16x32_bf16 v[104:107], v[190:193], v[214:217], v[104:107]
	v_mfma_f32_16x16x32_bf16 v[96:99], v[198:201], v[214:217], v[96:99]
	v_mfma_f32_16x16x32_bf16 v[88:91], v[190:193], v[226:229], v[88:91]
	v_mfma_f32_16x16x32_bf16 v[80:83], v[198:201], v[226:229], v[80:83]
	v_mfma_f32_16x16x32_bf16 v[72:75], v[190:193], v[236:239], v[72:75]
	v_mfma_f32_16x16x32_bf16 v[64:67], v[198:201], v[236:239], v[64:67]
	s_barrier
; #define PG8_STAGE(bufoff, gbase, voff) do { _Pragma("unroll") for (int _i = 0; _i < 2; ++_i) \
;         __builtin_amdgcn_global_load_lds((const unsigned*)((const char*)(gbase) + (voff)[_i]), (PG8_LAS unsigned*)(lds + (bufoff) + ldsw + _i * 8192), 16, 0, 0); } while (0)
; #define PG8_LDA(dst, b, h) do { _Pragma("unroll") for (int m = 0; m < 4; ++m) _Pragma("unroll") for (int k = 0; k < 2; ++k) dst[m][k] = *(const PG8_LAS bf16x8*)(lds + PG8_SA(b, h) + aoff + m * 2048 + k * 1024); } while (0)
; #define PG8_MMA(ai, bj, At, Bt) do { __builtin_amdgcn_s_setprio(1); _Pragma("unroll") for (int m = 0; m < 4; ++m) _Pragma("unroll") for (int n = 0; n < 2; ++n) _Pragma("unroll") for (int k = 0; k < 2; ++k) \
;         acc[ai][bj][m][n] = __builtin_amdgcn_mfma_f32_16x16x32_bf16(Bt[n][k], At[m][k], acc[ai][bj][m][n], 0, 0, 0); __builtin_amdgcn_s_setprio(0); } while (0)
; #define PG8_WAIT_V(n) asm volatile("s_waitcnt vmcnt(" #n ")" ::: "memory")
; #define PG8_WAIT_L(n) asm volatile("s_waitcnt lgkmcnt(" #n ")" ::: "memory")
; #define PG8_BAR __builtin_amdgcn_s_barrier()
; #define PG8_SCHED __builtin_amdgcn_sched_barrier(0)
; template <class Epi, class Sched, bool ALIGN_EPI = false, bool SP2 = false>
; __device__ __forceinline__ void gemm_phase(PG8_LAS unsigned char* lds, const Gemm g, const Sched& S, const Epi& E) {
;     ...
;             PG8_LDA(At, 1, 1); PG8_STAGE(PG8_SB(1, 0), b3, voffB); PG8_STAGE(PG8_SB(1, 1), b3 + hstep, voffB); PG8_STAGE(PG8_SA(1, 0), a3, voffA);
;             PG8_WAIT_V(8); PG8_WAIT_L(0); PG8_BAR; PG8_MMA(1, 0, At, B0); PG8_MMA(1, 1, At, B1); PG8_BAR; PG8_SCHED;
;     ...
;         if constexpr (ALIGN_EPI) { if (wr == 0) PG8_BAR; }
;         if constexpr (!Epi::AFTER_DRAIN) { E(acc, cur, wr, wc, fr, fq); S.done(cur); }
;         if (!has_next) break;
	s_add_i32 s77, s77, s71
	v_lshl_add_u64 v[168:169], v[168:169], 0, s[54:55]
	s_mov_b32 m0, s77
	ds_read_b128 v[202:205], v175 offset:49152
	ds_read_b128 v[206:209], v175 offset:50176
	ds_read_b128 v[210:213], v175 offset:51200
	ds_read_b128 v[214:217], v175 offset:52224
	ds_read_b128 v[218:221], v175 offset:53248
	ds_read_b128 v[226:229], v175 offset:54272
	ds_read_b128 v[230:233], v175 offset:55296
	ds_read_b128 v[236:239], v175 offset:56320
	global_load_lds_dwordx4 v[168:169], off
	s_add_i32 m0, s77, 0x2000
	s_add_u32 s84, s84, 0x40080
	v_lshl_add_u64 v[168:169], v[178:179], 0, s[54:55]
	s_addc_u32 s85, s85, 0
	s_add_i32 s77, s88, s71
	global_load_lds_dwordx4 v[168:169], off
	v_lshl_add_u64 v[168:169], s[84:85], 0, v[142:143]
	s_mov_b32 m0, s77
	s_nop 0
	global_load_lds_dwordx4 v[168:169], off
	v_lshl_add_u64 v[244:245], s[84:85], 0, v[146:147]
	v_lshl_add_u64 v[246:247], v[222:223], 0, s[54:55]
	v_lshl_add_u64 v[168:169], v[240:241], 0, s[54:55]
	s_waitcnt vmcnt(5)
	s_waitcnt lgkmcnt(0)
	s_barrier
	s_waitcnt lgkmcnt(0)
	v_mfma_f32_16x16x32_bf16 v[60:63], v[128:131], v[202:205], v[60:63]
	v_mfma_f32_16x16x32_bf16 v[52:55], v[136:139], v[202:205], v[52:55]
	v_mfma_f32_16x16x32_bf16 v[44:47], v[128:131], v[210:213], v[44:47]
	v_mfma_f32_16x16x32_bf16 v[36:39], v[136:139], v[210:213], v[36:39]
	s_add_i32 m0, s77, 0x2000
	v_mfma_f32_16x16x32_bf16 v[28:31], v[128:131], v[218:221], v[28:31]
	global_load_lds_dwordx4 v[244:245], off
	v_mfma_f32_16x16x32_bf16 v[20:23], v[136:139], v[218:221], v[20:23]
	v_mfma_f32_16x16x32_bf16 v[12:15], v[128:131], v[230:233], v[12:15]
	v_mfma_f32_16x16x32_bf16 v[4:7], v[136:139], v[230:233], v[4:7]
	v_mfma_f32_16x16x32_bf16 v[60:63], v[132:135], v[206:209], v[60:63]
	v_mfma_f32_16x16x32_bf16 v[52:55], v[182:185], v[206:209], v[52:55]
	v_mfma_f32_16x16x32_bf16 v[44:47], v[132:135], v[214:217], v[44:47]
	v_mfma_f32_16x16x32_bf16 v[36:39], v[182:185], v[214:217], v[36:39]
	s_mov_b32 m0, s33
	v_mfma_f32_16x16x32_bf16 v[28:31], v[132:135], v[226:229], v[28:31]
	global_load_lds_dwordx4 v[246:247], off
	v_mfma_f32_16x16x32_bf16 v[20:23], v[182:185], v[226:229], v[20:23]
	v_mfma_f32_16x16x32_bf16 v[12:15], v[132:135], v[236:239], v[12:15]
	v_mfma_f32_16x16x32_bf16 v[4:7], v[182:185], v[236:239], v[4:7]
	v_mfma_f32_16x16x32_bf16 v[56:59], v[186:189], v[202:205], v[56:59]
	v_mfma_f32_16x16x32_bf16 v[48:51], v[194:197], v[202:205], v[48:51]
	v_mfma_f32_16x16x32_bf16 v[40:43], v[186:189], v[210:213], v[40:43]
	v_mfma_f32_16x16x32_bf16 v[32:35], v[194:197], v[210:213], v[32:35]
	s_mov_b32 m0, s30
	v_mfma_f32_16x16x32_bf16 v[24:27], v[186:189], v[218:221], v[24:27]
	global_load_lds_dwordx4 v[168:169], off
	v_mfma_f32_16x16x32_bf16 v[16:19], v[194:197], v[218:221], v[16:19]
	v_mfma_f32_16x16x32_bf16 v[8:11], v[186:189], v[230:233], v[8:11]
	v_mfma_f32_16x16x32_bf16 v[0:3], v[194:197], v[230:233], v[0:3]
	v_mfma_f32_16x16x32_bf16 v[56:59], v[190:193], v[206:209], v[56:59]
	v_mfma_f32_16x16x32_bf16 v[48:51], v[198:201], v[206:209], v[48:51]
	v_mfma_f32_16x16x32_bf16 v[40:43], v[190:193], v[214:217], v[40:43]
	v_mfma_f32_16x16x32_bf16 v[32:35], v[198:201], v[214:217], v[32:35]
	v_mfma_f32_16x16x32_bf16 v[24:27], v[190:193], v[226:229], v[24:27]
	v_mfma_f32_16x16x32_bf16 v[16:19], v[198:201], v[226:229], v[16:19]
	v_mfma_f32_16x16x32_bf16 v[8:11], v[190:193], v[236:239], v[8:11]
	v_mfma_f32_16x16x32_bf16 v[0:3], v[198:201], v[236:239], v[0:3]
	s_barrier
	s_add_i32 s75, s75, 2
	s_add_u32 s82, s82, 0x100
	s_addc_u32 s83, s83, 0
	s_add_u32 s44, s44, 0x100
	s_addc_u32 s45, s45, 0
	s_cmp_gt_u32 s75, 13
	s_cbranch_scc0 .LBB0_387
	s_setprio 0
	s_and_b64 vcc, exec, s[56:57]
	s_cbranch_vccz .LBB0_390
	s_barrier

; #define PG8_STAGE(bufoff, gbase, voff) do { _Pragma("unroll") for (int _i = 0; _i < 2; ++_i) \
;         __builtin_amdgcn_global_load_lds((const unsigned*)((const char*)(gbase) + (voff)[_i]), (PG8_LAS unsigned*)(lds + (bufoff) + ldsw + _i * 8192), 16, 0, 0); } while (0)
; #define PG8_LDA(dst, b, h) do { _Pragma("unroll") for (int m = 0; m < 4; ++m) _Pragma("unroll") for (int k = 0; k < 2; ++k) dst[m][k] = *(const PG8_LAS bf16x8*)(lds + PG8_SA(b, h) + aoff + m * 2048 + k * 1024); } while (0)
; #define PG8_LDB(dst, b, h) do { _Pragma("unroll") for (int n = 0; n < 2; ++n) _Pragma("unroll") for (int k = 0; k < 2; ++k) dst[n][k] = *(const PG8_LAS bf16x8*)(lds + PG8_SB(b, h) + boff + n * 2048 + k * 1024); } while (0)
; #define PG8_WAIT_V(n) asm volatile("s_waitcnt vmcnt(" #n ")" ::: "memory")
; #define PG8_WAIT_L(n) asm volatile("s_waitcnt lgkmcnt(" #n ")" ::: "memory")
; template <class Epi, class Sched, bool ALIGN_EPI = false, bool SP2 = false>
; __device__ __forceinline__ void gemm_phase(PG8_LAS unsigned char* lds, const Gemm g, const Sched& S, const Epi& E) {
;     ...
;         const bool has_next = S.next(ui + 1, nxt);
;         const char* nA = has_next ? (const char*)g.A + (size_t)nxt.pm * tstep : cA; const char* nB = has_next ? (const char*)g.Bt + (size_t)nxt.pn * tstep : cB;
;         asm volatile(".p2align 6" ::: "memory");
;         for (int t = 0; t < nt; t += 2) {
;             const bool last = (t == nt - 2);
;             const char* a1 = cA + (size_t)(t + 1) * kstep;
;             const char* a2 = last ? nA : cA + (size_t)(t + 2) * kstep; const char* b2 = last ? nB : cB + (size_t)(t + 2) * kstep;
;             const char* a3 = a2 + kstep; const char* b3 = b2 + kstep;
;             if (last && has_next) S.a_ready(nxt);
;             if constexpr (SP2) {
;             PG8_LDB(B0, 0, 0); PG8_LDB(B1, 0, 1); PG8_SCHED; PG8_LDA(At, 0, 0); PG8_STAGE(PG8_SA(1, 1), a1 + hstep, voffA);
;             PG8_WAIT_V(8); PG8_WAIT_L(0); PG8_BAR; PG8_MMA(0, 0, At, B0); PG8_MMA(0, 1, At, B1); PG8_BAR; PG8_SCHED;
;     ...
; #pragma unroll
;         for (int a = 0; a < 2; ++a)
; #pragma unroll
;             for (int b = 0; b < 2; ++b)
; #pragma unroll
;                 for (int m = 0; m < 4; ++m)
; #pragma unroll
;                     for (int n = 0; n < 2; ++n) acc[a][b][m][n] = (f32x4){0.f, 0.f, 0.f, 0.f};
;         cur = nxt; cA = nA; cB = nB; ++ui;
.LBB0_749:
	s_ashr_i32 s19, s18, 31
	s_lshl_b64 s[20:21], s[18:19], 19
	s_add_u32 s20, s26, s20
	s_addc_u32 s21, s27, s21
	s_and_b64 s[56:57], s[4:5], exec
	s_cselect_b32 s19, s21, s63
	s_cselect_b32 s56, s20, s62
	s_ashr_i32 s17, s16, 31
	s_lshl_b64 s[58:59], s[16:17], 19
	s_add_u32 s58, s46, s58
	s_addc_u32 s59, s47, s59
	s_and_b64 s[66:67], s[4:5], exec
	s_cselect_b32 s17, s59, s65
	s_cselect_b32 s57, s58, s64
	s_add_u32 s62, s62, 0x40080
	.p2align 6
	s_addc_u32 s63, s63, 0
	s_add_u32 s61, s64, 0x100
	v_mov_b32_e32 v0, 0
	s_addc_u32 s71, s65, 0
	s_mov_b32 s72, -2
	s_waitcnt lgkmcnt(0)
	v_mov_b32_e32 v1, v0
	v_mov_b32_e32 v2, v0
	v_mov_b32_e32 v3, v0
	v_mov_b32_e32 v4, v0
	v_mov_b32_e32 v5, v0
	v_mov_b32_e32 v6, v0
	v_mov_b32_e32 v7, v0
	v_mov_b32_e32 v16, v0
	v_mov_b32_e32 v17, v0
	v_mov_b32_e32 v18, v0
	v_mov_b32_e32 v19, v0
	v_mov_b32_e32 v20, v0
	v_mov_b32_e32 v21, v0
	v_mov_b32_e32 v22, v0
	v_mov_b32_e32 v23, v0
	v_mov_b32_e32 v32, v0
	v_mov_b32_e32 v33, v0
	v_mov_b32_e32 v34, v0
	v_mov_b32_e32 v35, v0
	v_mov_b32_e32 v36, v0
	v_mov_b32_e32 v37, v0
	v_mov_b32_e32 v38, v0
	v_mov_b32_e32 v39, v0
	v_mov_b32_e32 v48, v0
	v_mov_b32_e32 v49, v0
	v_mov_b32_e32 v50, v0
	v_mov_b32_e32 v51, v0
	v_mov_b32_e32 v52, v0
	v_mov_b32_e32 v53, v0
	v_mov_b32_e32 v54, v0
	v_mov_b32_e32 v55, v0
	v_mov_b32_e32 v8, v0
	v_mov_b32_e32 v9, v0
	v_mov_b32_e32 v10, v0
	v_mov_b32_e32 v11, v0
	v_mov_b32_e32 v12, v0
	v_mov_b32_e32 v13, v0
	v_mov_b32_e32 v14, v0
	v_mov_b32_e32 v15, v0
	v_mov_b32_e32 v24, v0
	v_mov_b32_e32 v25, v0
	v_mov_b32_e32 v26, v0
	v_mov_b32_e32 v27, v0
	v_mov_b32_e32 v28, v0
	v_mov_b32_e32 v29, v0
	v_mov_b32_e32 v30, v0
	v_mov_b32_e32 v31, v0
	v_mov_b32_e32 v40, v0
	v_mov_b32_e32 v41, v0
	v_mov_b32_e32 v42, v0
	v_mov_b32_e32 v43, v0
	v_mov_b32_e32 v44, v0
	v_mov_b32_e32 v45, v0
	v_mov_b32_e32 v46, v0
	v_mov_b32_e32 v47, v0
	v_mov_b32_e32 v56, v0
	v_mov_b32_e32 v57, v0
	v_mov_b32_e32 v58, v0
	v_mov_b32_e32 v59, v0
	v_mov_b32_e32 v60, v0
	v_mov_b32_e32 v61, v0
	v_mov_b32_e32 v62, v0
	v_mov_b32_e32 v63, v0
	v_mov_b32_e32 v64, v0
	v_mov_b32_e32 v65, v0
	v_mov_b32_e32 v66, v0
	v_mov_b32_e32 v67, v0
	v_mov_b32_e32 v68, v0
	v_mov_b32_e32 v69, v0
	v_mov_b32_e32 v70, v0
	v_mov_b32_e32 v71, v0
	v_mov_b32_e32 v80, v0
	v_mov_b32_e32 v81, v0
	v_mov_b32_e32 v82, v0
	v_mov_b32_e32 v83, v0
	v_mov_b32_e32 v84, v0
	v_mov_b32_e32 v85, v0
	v_mov_b32_e32 v86, v0
	v_mov_b32_e32 v87, v0
	v_mov_b32_e32 v96, v0
	v_mov_b32_e32 v97, v0
	v_mov_b32_e32 v98, v0
	v_mov_b32_e32 v99, v0
	v_mov_b32_e32 v100, v0
	v_mov_b32_e32 v101, v0
	v_mov_b32_e32 v102, v0
	v_mov_b32_e32 v103, v0
	v_mov_b32_e32 v112, v0
	v_mov_b32_e32 v113, v0
	v_mov_b32_e32 v114, v0
	v_mov_b32_e32 v115, v0
	v_mov_b32_e32 v116, v0
	v_mov_b32_e32 v117, v0
	v_mov_b32_e32 v118, v0
	v_mov_b32_e32 v119, v0
	v_mov_b32_e32 v72, v0
	v_mov_b32_e32 v73, v0
	v_mov_b32_e32 v74, v0
	v_mov_b32_e32 v75, v0
	v_mov_b32_e32 v76, v0
	v_mov_b32_e32 v77, v0
	v_mov_b32_e32 v78, v0
	v_mov_b32_e32 v79, v0
	v_mov_b32_e32 v88, v0
	v_mov_b32_e32 v89, v0
	v_mov_b32_e32 v90, v0
	v_mov_b32_e32 v91, v0
	v_mov_b32_e32 v92, v0
	v_mov_b32_e32 v93, v0
	v_mov_b32_e32 v94, v0
	v_mov_b32_e32 v95, v0
	v_mov_b32_e32 v104, v0
	v_mov_b32_e32 v105, v0
	v_mov_b32_e32 v106, v0
	v_mov_b32_e32 v107, v0
	v_mov_b32_e32 v108, v0
	v_mov_b32_e32 v109, v0
	v_mov_b32_e32 v110, v0
	v_mov_b32_e32 v111, v0
	v_mov_b32_e32 v120, v0
	v_mov_b32_e32 v121, v0
	v_mov_b32_e32 v122, v0
	v_mov_b32_e32 v123, v0
	v_mov_b32_e32 v124, v0
	v_mov_b32_e32 v125, v0
	v_mov_b32_e32 v126, v0
	v_mov_b32_e32 v127, v0
	s_cmp_eq_u64 s[14:15], 0
	s_cbranch_scc0 .Lprio_750
	s_setprio 1
.Lprio_750:
.LBB0_750:
	ds_read_b128 v[144:147], v151
	ds_read_b128 v[156:159], v151 offset:1024
	ds_read_b128 v[160:163], v151 offset:2048
	ds_read_b128 v[164:167], v151 offset:3072
	ds_read_b128 v[168:171], v152
	ds_read_b128 v[172:175], v152 offset:1024
	ds_read_b128 v[176:179], v152 offset:2048
	ds_read_b128 v[180:183], v152 offset:3072
	s_add_u32 s64, s62, 0xfffc0080
	s_addc_u32 s65, s63, -1
	s_cmp_eq_u32 s72, 12
	s_cselect_b32 s67, s19, s65
	s_cselect_b32 s66, s56, s64
	s_cselect_b32 s65, s17, s71
	s_cselect_b32 s64, s57, s61
	v_lshl_add_u64 v[216:217], s[62:63], 0, v[136:137]
	s_add_i32 m0, s22, 0xc000
	ds_read_b128 v[184:187], v153
	ds_read_b128 v[188:191], v153 offset:1024
	ds_read_b128 v[192:195], v153 offset:2048
	ds_read_b128 v[196:199], v153 offset:3072
	ds_read_b128 v[200:203], v153 offset:4096
	ds_read_b128 v[204:207], v153 offset:5120
	ds_read_b128 v[208:211], v153 offset:6144
	ds_read_b128 v[212:215], v153 offset:7168
	global_load_lds_dwordx4 v[216:217], off
	v_lshl_add_u64 v[216:217], s[62:63], 0, v[138:139]
	s_add_i32 m0, s22, 0xe000
	s_nop 0
	global_load_lds_dwordx4 v[216:217], off
	s_waitcnt vmcnt(8)
	s_waitcnt lgkmcnt(0)
	s_barrier
; #define PG8_STAGE(bufoff, gbase, voff) do { _Pragma("unroll") for (int _i = 0; _i < 2; ++_i) \
;         __builtin_amdgcn_global_load_lds((const unsigned*)((const char*)(gbase) + (voff)[_i]), (PG8_LAS unsigned*)(lds + (bufoff) + ldsw + _i * 8192), 16, 0, 0); } while (0)
; #define PG8_LDA(dst, b, h) do { _Pragma("unroll") for (int m = 0; m < 4; ++m) _Pragma("unroll") for (int k = 0; k < 2; ++k) dst[m][k] = *(const PG8_LAS bf16x8*)(lds + PG8_SA(b, h) + aoff + m * 2048 + k * 1024); } while (0)
; #define PG8_LDB(dst, b, h) do { _Pragma("unroll") for (int n = 0; n < 2; ++n) _Pragma("unroll") for (int k = 0; k < 2; ++k) dst[n][k] = *(const PG8_LAS bf16x8*)(lds + PG8_SB(b, h) + boff + n * 2048 + k * 1024); } while (0)
; #define PG8_MMA(ai, bj, At, Bt) do { __builtin_amdgcn_s_setprio(1); _Pragma("unroll") for (int m = 0; m < 4; ++m) _Pragma("unroll") for (int n = 0; n < 2; ++n) _Pragma("unroll") for (int k = 0; k < 2; ++k) \
;         acc[ai][bj][m][n] = __builtin_amdgcn_mfma_f32_16x16x32_bf16(Bt[n][k], At[m][k], acc[ai][bj][m][n], 0, 0, 0); __builtin_amdgcn_s_setprio(0); } while (0)
; #define PG8_WAIT_V(n) asm volatile("s_waitcnt vmcnt(" #n ")" ::: "memory")
; #define PG8_WAIT_L(n) asm volatile("s_waitcnt lgkmcnt(" #n ")" ::: "memory")
; #define PG8_BAR __builtin_amdgcn_s_barrier()
; #define PG8_SCHED __builtin_amdgcn_sched_barrier(0)
; template <class Epi, class Sched, bool ALIGN_EPI = false, bool SP2 = false>
; __device__ __forceinline__ void gemm_phase(PG8_LAS unsigned char* lds, const Gemm g, const Sched& S, const Epi& E) {
;     ...
;             PG8_WAIT_V(8); PG8_WAIT_L(0); PG8_BAR; PG8_MMA(0, 0, At, B0); PG8_MMA(0, 1, At, B1); PG8_BAR; PG8_SCHED;
;             PG8_LDA(At, 0, 1); PG8_STAGE(PG8_SB(0, 0), b2, voffB); PG8_STAGE(PG8_SB(0, 1), b2 + hstep, voffB); PG8_STAGE(PG8_SA(0, 0), a2, voffA);
;             PG8_WAIT_V(8); PG8_WAIT_L(0); PG8_BAR; PG8_MMA(1, 0, At, B0); PG8_MMA(1, 1, At, B1); PG8_BAR; PG8_SCHED;
;             PG8_LDB(B0, 1, 0); PG8_LDB(B1, 1, 1); PG8_SCHED; PG8_LDA(At, 1, 0); PG8_STAGE(PG8_SA(0, 1), a2 + hstep, voffA);
;             PG8_WAIT_V(8); PG8_WAIT_L(0); PG8_BAR; PG8_MMA(0, 0, At, B0); PG8_MMA(0, 1, At, B1); PG8_BAR; PG8_SCHED;
	s_waitcnt lgkmcnt(0)
	v_mfma_f32_16x16x32_bf16 v[124:127], v[144:147], v[184:187], v[124:127]
	v_mfma_f32_16x16x32_bf16 v[120:123], v[160:163], v[184:187], v[120:123]
	v_mfma_f32_16x16x32_bf16 v[108:111], v[144:147], v[192:195], v[108:111]
	v_mfma_f32_16x16x32_bf16 v[104:107], v[160:163], v[192:195], v[104:107]
	v_mfma_f32_16x16x32_bf16 v[92:95], v[144:147], v[200:203], v[92:95]
	v_mfma_f32_16x16x32_bf16 v[88:91], v[160:163], v[200:203], v[88:91]
	v_mfma_f32_16x16x32_bf16 v[76:79], v[144:147], v[208:211], v[76:79]
	v_mfma_f32_16x16x32_bf16 v[72:75], v[160:163], v[208:211], v[72:75]
	v_mfma_f32_16x16x32_bf16 v[124:127], v[156:159], v[188:191], v[124:127]
	v_mfma_f32_16x16x32_bf16 v[120:123], v[164:167], v[188:191], v[120:123]
	v_mfma_f32_16x16x32_bf16 v[108:111], v[156:159], v[196:199], v[108:111]
	v_mfma_f32_16x16x32_bf16 v[104:107], v[164:167], v[196:199], v[104:107]
	v_mfma_f32_16x16x32_bf16 v[92:95], v[156:159], v[204:207], v[92:95]
	v_mfma_f32_16x16x32_bf16 v[88:91], v[164:167], v[204:207], v[88:91]
	v_mfma_f32_16x16x32_bf16 v[76:79], v[156:159], v[212:215], v[76:79]
	v_mfma_f32_16x16x32_bf16 v[72:75], v[164:167], v[212:215], v[72:75]
	v_mfma_f32_16x16x32_bf16 v[116:119], v[168:171], v[184:187], v[116:119]
	v_mfma_f32_16x16x32_bf16 v[112:115], v[176:179], v[184:187], v[112:115]
	v_mfma_f32_16x16x32_bf16 v[100:103], v[168:171], v[192:195], v[100:103]
	v_mfma_f32_16x16x32_bf16 v[96:99], v[176:179], v[192:195], v[96:99]
	v_mfma_f32_16x16x32_bf16 v[84:87], v[168:171], v[200:203], v[84:87]
	v_mfma_f32_16x16x32_bf16 v[80:83], v[176:179], v[200:203], v[80:83]
	v_mfma_f32_16x16x32_bf16 v[68:71], v[168:171], v[208:211], v[68:71]
	v_mfma_f32_16x16x32_bf16 v[64:67], v[176:179], v[208:211], v[64:67]
	v_mfma_f32_16x16x32_bf16 v[116:119], v[172:175], v[188:191], v[116:119]
	v_mfma_f32_16x16x32_bf16 v[112:115], v[180:183], v[188:191], v[112:115]
	v_mfma_f32_16x16x32_bf16 v[100:103], v[172:175], v[196:199], v[100:103]
	v_mfma_f32_16x16x32_bf16 v[96:99], v[180:183], v[196:199], v[96:99]
	v_mfma_f32_16x16x32_bf16 v[84:87], v[172:175], v[204:207], v[84:87]
	v_mfma_f32_16x16x32_bf16 v[80:83], v[180:183], v[204:207], v[80:83]
	v_mfma_f32_16x16x32_bf16 v[68:71], v[172:175], v[212:215], v[68:71]
	v_mfma_f32_16x16x32_bf16 v[64:67], v[180:183], v[212:215], v[64:67]
	s_barrier
	s_add_i32 s73, s68, s2
	v_lshl_add_u64 v[216:217], s[64:65], 0, v[130:131]
	s_mov_b32 m0, s73
	ds_read_b128 v[184:187], v153 offset:16384
	ds_read_b128 v[188:191], v153 offset:17408
	ds_read_b128 v[192:195], v153 offset:18432
	ds_read_b128 v[196:199], v153 offset:19456
	ds_read_b128 v[200:203], v153 offset:20480
	ds_read_b128 v[204:207], v153 offset:21504
	ds_read_b128 v[208:211], v153 offset:22528
	ds_read_b128 v[212:215], v153 offset:23552
	global_load_lds_dwordx4 v[216:217], off
	s_add_i32 m0, s73, 0x2000
	s_add_u32 s74, s64, 0x40000
	v_lshl_add_u64 v[218:219], s[64:65], 0, v[134:135]
	s_addc_u32 s75, s65, 0
	s_add_i32 s73, s69, s2
	global_load_lds_dwordx4 v[218:219], off
	v_lshl_add_u64 v[220:221], s[74:75], 0, v[130:131]
	s_mov_b32 m0, s73
	v_lshl_add_u64 v[222:223], s[66:67], 0, v[132:133]
	global_load_lds_dwordx4 v[220:221], off
	v_lshl_add_u64 v[244:245], s[74:75], 0, v[134:135]
	v_lshl_add_u64 v[220:221], s[66:67], 0, v[128:129]
	s_waitcnt vmcnt(5)
	s_waitcnt lgkmcnt(0)
	s_barrier
	s_waitcnt lgkmcnt(0)
	v_mfma_f32_16x16x32_bf16 v[60:63], v[144:147], v[184:187], v[60:63]
	v_mfma_f32_16x16x32_bf16 v[56:59], v[160:163], v[184:187], v[56:59]
	v_mfma_f32_16x16x32_bf16 v[44:47], v[144:147], v[192:195], v[44:47]
	v_mfma_f32_16x16x32_bf16 v[40:43], v[160:163], v[192:195], v[40:43]
	s_add_i32 m0, s73, 0x2000
	v_mfma_f32_16x16x32_bf16 v[28:31], v[144:147], v[200:203], v[28:31]
	global_load_lds_dwordx4 v[244:245], off
	v_mfma_f32_16x16x32_bf16 v[24:27], v[160:163], v[200:203], v[24:27]
	v_mfma_f32_16x16x32_bf16 v[12:15], v[144:147], v[208:211], v[12:15]
	v_mfma_f32_16x16x32_bf16 v[8:11], v[160:163], v[208:211], v[8:11]
	v_mfma_f32_16x16x32_bf16 v[60:63], v[156:159], v[188:191], v[60:63]
	v_mfma_f32_16x16x32_bf16 v[56:59], v[164:167], v[188:191], v[56:59]
	v_mfma_f32_16x16x32_bf16 v[44:47], v[156:159], v[196:199], v[44:47]
	v_mfma_f32_16x16x32_bf16 v[40:43], v[164:167], v[196:199], v[40:43]
	s_mov_b32 m0, s22
	v_mfma_f32_16x16x32_bf16 v[28:31], v[156:159], v[204:207], v[28:31]
	global_load_lds_dwordx4 v[220:221], off
	v_mfma_f32_16x16x32_bf16 v[24:27], v[164:167], v[204:207], v[24:27]
	v_mfma_f32_16x16x32_bf16 v[12:15], v[156:159], v[212:215], v[12:15]
	v_mfma_f32_16x16x32_bf16 v[8:11], v[164:167], v[212:215], v[8:11]
	v_mfma_f32_16x16x32_bf16 v[52:55], v[168:171], v[184:187], v[52:55]
	v_mfma_f32_16x16x32_bf16 v[48:51], v[176:179], v[184:187], v[48:51]
	v_mfma_f32_16x16x32_bf16 v[36:39], v[168:171], v[192:195], v[36:39]
	v_mfma_f32_16x16x32_bf16 v[32:35], v[176:179], v[192:195], v[32:35]
	s_mov_b32 m0, s23
	v_mfma_f32_16x16x32_bf16 v[20:23], v[168:171], v[200:203], v[20:23]
	global_load_lds_dwordx4 v[222:223], off
	v_mfma_f32_16x16x32_bf16 v[16:19], v[176:179], v[200:203], v[16:19]
	v_mfma_f32_16x16x32_bf16 v[4:7], v[168:171], v[208:211], v[4:7]
	v_mfma_f32_16x16x32_bf16 v[0:3], v[176:179], v[208:211], v[0:3]
	v_mfma_f32_16x16x32_bf16 v[52:55], v[172:175], v[188:191], v[52:55]
	v_mfma_f32_16x16x32_bf16 v[48:51], v[180:183], v[188:191], v[48:51]
	v_mfma_f32_16x16x32_bf16 v[36:39], v[172:175], v[196:199], v[36:39]
	v_mfma_f32_16x16x32_bf16 v[32:35], v[180:183], v[196:199], v[32:35]
	v_mfma_f32_16x16x32_bf16 v[20:23], v[172:175], v[204:207], v[20:23]
	v_mfma_f32_16x16x32_bf16 v[16:19], v[180:183], v[204:207], v[16:19]
	v_mfma_f32_16x16x32_bf16 v[4:7], v[172:175], v[212:215], v[4:7]
	v_mfma_f32_16x16x32_bf16 v[0:3], v[180:183], v[212:215], v[0:3]
	s_barrier
; #define PG8_STAGE(bufoff, gbase, voff) do { _Pragma("unroll") for (int _i = 0; _i < 2; ++_i) \
;         __builtin_amdgcn_global_load_lds((const unsigned*)((const char*)(gbase) + (voff)[_i]), (PG8_LAS unsigned*)(lds + (bufoff) + ldsw + _i * 8192), 16, 0, 0); } while (0)
; #define PG8_LDA(dst, b, h) do { _Pragma("unroll") for (int m = 0; m < 4; ++m) _Pragma("unroll") for (int k = 0; k < 2; ++k) dst[m][k] = *(const PG8_LAS bf16x8*)(lds + PG8_SA(b, h) + aoff + m * 2048 + k * 1024); } while (0)
; #define PG8_LDB(dst, b, h) do { _Pragma("unroll") for (int n = 0; n < 2; ++n) _Pragma("unroll") for (int k = 0; k < 2; ++k) dst[n][k] = *(const PG8_LAS bf16x8*)(lds + PG8_SB(b, h) + boff + n * 2048 + k * 1024); } while (0)
; #define PG8_MMA(ai, bj, At, Bt) do { __builtin_amdgcn_s_setprio(1); _Pragma("unroll") for (int m = 0; m < 4; ++m) _Pragma("unroll") for (int n = 0; n < 2; ++n) _Pragma("unroll") for (int k = 0; k < 2; ++k) \
;         acc[ai][bj][m][n] = __builtin_amdgcn_mfma_f32_16x16x32_bf16(Bt[n][k], At[m][k], acc[ai][bj][m][n], 0, 0, 0); __builtin_amdgcn_s_setprio(0); } while (0)
; #define PG8_WAIT_V(n) asm volatile("s_waitcnt vmcnt(" #n ")" ::: "memory")
; #define PG8_WAIT_L(n) asm volatile("s_waitcnt lgkmcnt(" #n ")" ::: "memory")
; #define PG8_BAR __builtin_amdgcn_s_barrier()
; #define PG8_SCHED __builtin_amdgcn_sched_barrier(0)
; template <class Epi, class Sched, bool ALIGN_EPI = false, bool SP2 = false>
; __device__ __forceinline__ void gemm_phase(PG8_LAS unsigned char* lds, const Gemm g, const Sched& S, const Epi& E) {
;     ...
;             PG8_LDB(B0, 1, 0); PG8_LDB(B1, 1, 1); PG8_SCHED; PG8_LDA(At, 1, 0); PG8_STAGE(PG8_SA(0, 1), a2 + hstep, voffA);
;             PG8_WAIT_V(8); PG8_WAIT_L(0); PG8_BAR; PG8_MMA(0, 0, At, B0); PG8_MMA(0, 1, At, B1); PG8_BAR; PG8_SCHED;
	s_add_i32 s73, 0, 0x18000
	v_add_u32_e32 v155, s73, v149
	s_add_i32 s74, 0, 0x1c000
	ds_read_b128 v[144:147], v155
	ds_read_b128 v[156:159], v155 offset:1024
	ds_read_b128 v[160:163], v155 offset:2048
	ds_read_b128 v[164:167], v155 offset:3072
	v_add_u32_e32 v155, s74, v149
	ds_read_b128 v[168:171], v155
	ds_read_b128 v[172:175], v155 offset:1024
	ds_read_b128 v[176:179], v155 offset:2048
	ds_read_b128 v[180:183], v155 offset:3072
	s_add_u32 s66, s66, 0x40000
	s_addc_u32 s67, s67, 0
	s_mov_b32 m0, s30
	v_lshl_add_u64 v[226:227], s[66:67], 0, v[128:129]
	ds_read_b128 v[184:187], v153 offset:32768
	ds_read_b128 v[188:191], v153 offset:33792
	ds_read_b128 v[192:195], v153 offset:34816
	ds_read_b128 v[196:199], v153 offset:35840
	ds_read_b128 v[200:203], v153 offset:36864
	ds_read_b128 v[204:207], v153 offset:37888
	ds_read_b128 v[208:211], v153 offset:38912
	ds_read_b128 v[212:215], v153 offset:39936
	global_load_lds_dwordx4 v[226:227], off
	v_lshl_add_u64 v[226:227], s[66:67], 0, v[132:133]
	s_mov_b32 m0, s31
	s_nop 0
	global_load_lds_dwordx4 v[226:227], off
	s_waitcnt vmcnt(8)
	s_waitcnt lgkmcnt(0)
	s_barrier
	s_waitcnt lgkmcnt(0)
	v_mfma_f32_16x16x32_bf16 v[124:127], v[144:147], v[184:187], v[124:127]
	v_mfma_f32_16x16x32_bf16 v[120:123], v[160:163], v[184:187], v[120:123]
	v_mfma_f32_16x16x32_bf16 v[108:111], v[144:147], v[192:195], v[108:111]
	v_mfma_f32_16x16x32_bf16 v[104:107], v[160:163], v[192:195], v[104:107]
	v_mfma_f32_16x16x32_bf16 v[92:95], v[144:147], v[200:203], v[92:95]
	v_mfma_f32_16x16x32_bf16 v[88:91], v[160:163], v[200:203], v[88:91]
	v_mfma_f32_16x16x32_bf16 v[76:79], v[144:147], v[208:211], v[76:79]
	v_mfma_f32_16x16x32_bf16 v[72:75], v[160:163], v[208:211], v[72:75]
	v_mfma_f32_16x16x32_bf16 v[124:127], v[156:159], v[188:191], v[124:127]
	v_mfma_f32_16x16x32_bf16 v[120:123], v[164:167], v[188:191], v[120:123]
	v_mfma_f32_16x16x32_bf16 v[108:111], v[156:159], v[196:199], v[108:111]
	v_mfma_f32_16x16x32_bf16 v[104:107], v[164:167], v[196:199], v[104:107]
	v_mfma_f32_16x16x32_bf16 v[92:95], v[156:159], v[204:207], v[92:95]
	v_mfma_f32_16x16x32_bf16 v[88:91], v[164:167], v[204:207], v[88:91]
	v_mfma_f32_16x16x32_bf16 v[76:79], v[156:159], v[212:215], v[76:79]
	v_mfma_f32_16x16x32_bf16 v[72:75], v[164:167], v[212:215], v[72:75]
	v_mfma_f32_16x16x32_bf16 v[116:119], v[168:171], v[184:187], v[116:119]
	v_mfma_f32_16x16x32_bf16 v[112:115], v[176:179], v[184:187], v[112:115]
	v_mfma_f32_16x16x32_bf16 v[100:103], v[168:171], v[192:195], v[100:103]
	v_mfma_f32_16x16x32_bf16 v[96:99], v[176:179], v[192:195], v[96:99]
	v_mfma_f32_16x16x32_bf16 v[84:87], v[168:171], v[200:203], v[84:87]
	v_mfma_f32_16x16x32_bf16 v[80:83], v[176:179], v[200:203], v[80:83]
	v_mfma_f32_16x16x32_bf16 v[68:71], v[168:171], v[208:211], v[68:71]
	v_mfma_f32_16x16x32_bf16 v[64:67], v[176:179], v[208:211], v[64:67]
	v_mfma_f32_16x16x32_bf16 v[116:119], v[172:175], v[188:191], v[116:119]
	v_mfma_f32_16x16x32_bf16 v[112:115], v[180:183], v[188:191], v[112:115]
	v_mfma_f32_16x16x32_bf16 v[100:103], v[172:175], v[196:199], v[100:103]
	v_mfma_f32_16x16x32_bf16 v[96:99], v[180:183], v[196:199], v[96:99]
	v_mfma_f32_16x16x32_bf16 v[84:87], v[172:175], v[204:207], v[84:87]
	v_mfma_f32_16x16x32_bf16 v[80:83], v[180:183], v[204:207], v[80:83]
	v_mfma_f32_16x16x32_bf16 v[68:71], v[172:175], v[212:215], v[68:71]
	v_mfma_f32_16x16x32_bf16 v[64:67], v[180:183], v[212:215], v[64:67]
	s_barrier
; #define PG8_STAGE(bufoff, gbase, voff) do { _Pragma("unroll") for (int _i = 0; _i < 2; ++_i) \
;         __builtin_amdgcn_global_load_lds((const unsigned*)((const char*)(gbase) + (voff)[_i]), (PG8_LAS unsigned*)(lds + (bufoff) + ldsw + _i * 8192), 16, 0, 0); } while (0)
; #define PG8_LDA(dst, b, h) do { _Pragma("unroll") for (int m = 0; m < 4; ++m) _Pragma("unroll") for (int k = 0; k < 2; ++k) dst[m][k] = *(const PG8_LAS bf16x8*)(lds + PG8_SA(b, h) + aoff + m * 2048 + k * 1024); } while (0)
; #define PG8_MMA(ai, bj, At, Bt) do { __builtin_amdgcn_s_setprio(1); _Pragma("unroll") for (int m = 0; m < 4; ++m) _Pragma("unroll") for (int n = 0; n < 2; ++n) _Pragma("unroll") for (int k = 0; k < 2; ++k) \
;         acc[ai][bj][m][n] = __builtin_amdgcn_mfma_f32_16x16x32_bf16(Bt[n][k], At[m][k], acc[ai][bj][m][n], 0, 0, 0); __builtin_amdgcn_s_setprio(0); } while (0)
; #define PG8_WAIT_V(n) asm volatile("s_waitcnt vmcnt(" #n ")" ::: "memory")
; #define PG8_WAIT_L(n) asm volatile("s_waitcnt lgkmcnt(" #n ")" ::: "memory")
; #define PG8_BAR __builtin_amdgcn_s_barrier()
; #define PG8_SCHED __builtin_amdgcn_sched_barrier(0)
; template <class Epi, class Sched, bool ALIGN_EPI = false, bool SP2 = false>
; __device__ __forceinline__ void gemm_phase(PG8_LAS unsigned char* lds, const Gemm g, const Sched& S, const Epi& E) {
;     ...
;             PG8_LDA(At, 1, 1); PG8_STAGE(PG8_SB(1, 0), b3, voffB); PG8_STAGE(PG8_SB(1, 1), b3 + hstep, voffB); PG8_STAGE(PG8_SA(1, 0), a3, voffA);
;             PG8_WAIT_V(8); PG8_WAIT_L(0); PG8_BAR; PG8_MMA(1, 0, At, B0); PG8_MMA(1, 1, At, B1); PG8_BAR; PG8_SCHED;
;     ...
;         if constexpr (ALIGN_EPI) { if (wr == 0) PG8_BAR; }
;         if constexpr (!Epi::AFTER_DRAIN) { E(acc, cur, wr, wc, fr, fq); S.done(cur); }
;         if (!has_next) break;
	s_add_i32 s66, s73, s2
	v_lshl_add_u64 v[216:217], v[216:217], 0, s[12:13]
	s_mov_b32 m0, s66
	ds_read_b128 v[184:187], v153 offset:49152
	ds_read_b128 v[188:191], v153 offset:50176
	ds_read_b128 v[192:195], v153 offset:51200
	ds_read_b128 v[196:199], v153 offset:52224
	ds_read_b128 v[200:203], v153 offset:53248
	ds_read_b128 v[204:207], v153 offset:54272
	ds_read_b128 v[208:211], v153 offset:55296
	ds_read_b128 v[212:215], v153 offset:56320
	global_load_lds_dwordx4 v[216:217], off
	s_add_i32 m0, s66, 0x2000
	s_add_u32 s64, s64, 0x40080
	v_lshl_add_u64 v[216:217], v[218:219], 0, s[12:13]
	s_addc_u32 s65, s65, 0
	s_add_i32 s66, s74, s2
	global_load_lds_dwordx4 v[216:217], off
	v_lshl_add_u64 v[216:217], s[64:65], 0, v[130:131]
	s_mov_b32 m0, s66
	s_nop 0
	global_load_lds_dwordx4 v[216:217], off
	v_lshl_add_u64 v[244:245], s[64:65], 0, v[134:135]
	v_lshl_add_u64 v[246:247], v[220:221], 0, s[12:13]
	v_lshl_add_u64 v[216:217], v[222:223], 0, s[12:13]
	s_waitcnt vmcnt(5)
	s_waitcnt lgkmcnt(0)
	s_barrier
	s_waitcnt lgkmcnt(0)
	v_mfma_f32_16x16x32_bf16 v[60:63], v[144:147], v[184:187], v[60:63]
	v_mfma_f32_16x16x32_bf16 v[56:59], v[160:163], v[184:187], v[56:59]
	v_mfma_f32_16x16x32_bf16 v[44:47], v[144:147], v[192:195], v[44:47]
	v_mfma_f32_16x16x32_bf16 v[40:43], v[160:163], v[192:195], v[40:43]
	s_add_i32 m0, s66, 0x2000
	v_mfma_f32_16x16x32_bf16 v[28:31], v[144:147], v[200:203], v[28:31]
	global_load_lds_dwordx4 v[244:245], off
	v_mfma_f32_16x16x32_bf16 v[24:27], v[160:163], v[200:203], v[24:27]
	v_mfma_f32_16x16x32_bf16 v[12:15], v[144:147], v[208:211], v[12:15]
	v_mfma_f32_16x16x32_bf16 v[8:11], v[160:163], v[208:211], v[8:11]
	v_mfma_f32_16x16x32_bf16 v[60:63], v[156:159], v[188:191], v[60:63]
	v_mfma_f32_16x16x32_bf16 v[56:59], v[164:167], v[188:191], v[56:59]
	v_mfma_f32_16x16x32_bf16 v[44:47], v[156:159], v[196:199], v[44:47]
	v_mfma_f32_16x16x32_bf16 v[40:43], v[164:167], v[196:199], v[40:43]
	s_mov_b32 m0, s44
	v_mfma_f32_16x16x32_bf16 v[28:31], v[156:159], v[204:207], v[28:31]
	global_load_lds_dwordx4 v[246:247], off
	v_mfma_f32_16x16x32_bf16 v[24:27], v[164:167], v[204:207], v[24:27]
	v_mfma_f32_16x16x32_bf16 v[12:15], v[156:159], v[212:215], v[12:15]
	v_mfma_f32_16x16x32_bf16 v[8:11], v[164:167], v[212:215], v[8:11]
	v_mfma_f32_16x16x32_bf16 v[52:55], v[168:171], v[184:187], v[52:55]
	v_mfma_f32_16x16x32_bf16 v[48:51], v[176:179], v[184:187], v[48:51]
	v_mfma_f32_16x16x32_bf16 v[36:39], v[168:171], v[192:195], v[36:39]
	v_mfma_f32_16x16x32_bf16 v[32:35], v[176:179], v[192:195], v[32:35]
	s_mov_b32 m0, s45
	v_mfma_f32_16x16x32_bf16 v[20:23], v[168:171], v[200:203], v[20:23]
	global_load_lds_dwordx4 v[216:217], off
	v_mfma_f32_16x16x32_bf16 v[16:19], v[176:179], v[200:203], v[16:19]
	v_mfma_f32_16x16x32_bf16 v[4:7], v[168:171], v[208:211], v[4:7]
	v_mfma_f32_16x16x32_bf16 v[0:3], v[176:179], v[208:211], v[0:3]
	v_mfma_f32_16x16x32_bf16 v[52:55], v[172:175], v[188:191], v[52:55]
	v_mfma_f32_16x16x32_bf16 v[48:51], v[180:183], v[188:191], v[48:51]
	v_mfma_f32_16x16x32_bf16 v[36:39], v[172:175], v[196:199], v[36:39]
	v_mfma_f32_16x16x32_bf16 v[32:35], v[180:183], v[196:199], v[32:35]
	v_mfma_f32_16x16x32_bf16 v[20:23], v[172:175], v[204:207], v[20:23]
	v_mfma_f32_16x16x32_bf16 v[16:19], v[180:183], v[204:207], v[16:19]
	v_mfma_f32_16x16x32_bf16 v[4:7], v[172:175], v[212:215], v[4:7]
	v_mfma_f32_16x16x32_bf16 v[0:3], v[180:183], v[212:215], v[0:3]
	s_barrier
	s_add_i32 s72, s72, 2
	s_add_u32 s62, s62, 0x100
	s_addc_u32 s63, s63, 0
	s_add_u32 s61, s61, 0x100
	s_addc_u32 s71, s71, 0
	s_cmp_gt_u32 s72, 13
	s_cbranch_scc0 .LBB0_750
	s_setprio 0
	s_and_b64 vcc, exec, s[14:15]
	s_cbranch_vccz .LBB0_753
	s_barrier

; #define PG8_STAGE(bufoff, gbase, voff) do { _Pragma("unroll") for (int _i = 0; _i < 2; ++_i) \
;         __builtin_amdgcn_global_load_lds((const unsigned*)((const char*)(gbase) + (voff)[_i]), (PG8_LAS unsigned*)(lds + (bufoff) + ldsw + _i * 8192), 16, 0, 0); } while (0)
; #define PG8_LDA(dst, b, h) do { _Pragma("unroll") for (int m = 0; m < 4; ++m) _Pragma("unroll") for (int k = 0; k < 2; ++k) dst[m][k] = *(const PG8_LAS bf16x8*)(lds + PG8_SA(b, h) + aoff + m * 2048 + k * 1024); } while (0)
; #define PG8_LDB(dst, b, h) do { _Pragma("unroll") for (int n = 0; n < 2; ++n) _Pragma("unroll") for (int k = 0; k < 2; ++k) dst[n][k] = *(const PG8_LAS bf16x8*)(lds + PG8_SB(b, h) + boff + n * 2048 + k * 1024); } while (0)
; #define PG8_WAIT_V(n) asm volatile("s_waitcnt vmcnt(" #n ")" ::: "memory")
; #define PG8_WAIT_L(n) asm volatile("s_waitcnt lgkmcnt(" #n ")" ::: "memory")
; template <class Epi, class Sched, bool ALIGN_EPI = false, bool SP2 = false>
; __device__ __forceinline__ void gemm_phase(PG8_LAS unsigned char* lds, const Gemm g, const Sched& S, const Epi& E) {
;     ...
;         const bool has_next = S.next(ui + 1, nxt);
;         const char* nA = has_next ? (const char*)g.A + (size_t)nxt.pm * tstep : cA; const char* nB = has_next ? (const char*)g.Bt + (size_t)nxt.pn * tstep : cB;
;         asm volatile(".p2align 6" ::: "memory");
;         for (int t = 0; t < nt; t += 2) {
;             const bool last = (t == nt - 2);
;             const char* a1 = cA + (size_t)(t + 1) * kstep;
;             const char* a2 = last ? nA : cA + (size_t)(t + 2) * kstep; const char* b2 = last ? nB : cB + (size_t)(t + 2) * kstep;
;             const char* a3 = a2 + kstep; const char* b3 = b2 + kstep;
;             if (last && has_next) S.a_ready(nxt);
;             if constexpr (SP2) {
;             PG8_LDB(B0, 0, 0); PG8_LDB(B1, 0, 1); PG8_SCHED; PG8_LDA(At, 0, 0); PG8_STAGE(PG8_SA(1, 1), a1 + hstep, voffA);
;             PG8_WAIT_V(8); PG8_WAIT_L(0); PG8_BAR; PG8_MMA(0, 0, At, B0); PG8_MMA(0, 1, At, B1); PG8_BAR; PG8_SCHED;
;     ...
; #pragma unroll
;         for (int a = 0; a < 2; ++a)
; #pragma unroll
;             for (int b = 0; b < 2; ++b)
; #pragma unroll
;                 for (int m = 0; m < 4; ++m)
; #pragma unroll
;                     for (int n = 0; n < 2; ++n) acc[a][b][m][n] = (f32x4){0.f, 0.f, 0.f, 0.f};
;         cur = nxt; cA = nA; cB = nB; ++ui;
.LBB0_834:
	s_ashr_i32 s73, s72, 31
	s_lshl_b64 s[6:7], s[72:73], 19
	s_add_u32 s74, s40, s6
	s_addc_u32 s75, s41, s7
	s_and_b64 s[6:7], s[0:1], exec
	s_cselect_b32 s5, s75, s79
	s_cselect_b32 s12, s74, s78
	s_ashr_i32 s71, s70, 31
	s_lshl_b64 s[6:7], s[70:71], 19
	s_add_u32 s76, s42, s6
	s_addc_u32 s77, s43, s7
	s_and_b64 s[6:7], s[0:1], exec
	s_cselect_b32 s56, s77, s9
	s_cselect_b32 s57, s76, s8
	s_add_u32 s6, s78, 0x40080
	.p2align 6
	s_addc_u32 s7, s79, 0
	s_add_u32 s71, s8, 0x100
	v_mov_b32_e32 v0, 0
	s_addc_u32 s73, s9, 0
	s_mov_b32 s80, -2
	v_mov_b32_e32 v1, v0
	v_mov_b32_e32 v2, v0
	v_mov_b32_e32 v3, v0
	v_mov_b32_e32 v4, v0
	v_mov_b32_e32 v5, v0
	v_mov_b32_e32 v6, v0
	v_mov_b32_e32 v7, v0
	v_mov_b32_e32 v16, v0
	v_mov_b32_e32 v17, v0
	v_mov_b32_e32 v18, v0
	v_mov_b32_e32 v19, v0
	v_mov_b32_e32 v20, v0
	v_mov_b32_e32 v21, v0
	v_mov_b32_e32 v22, v0
	v_mov_b32_e32 v23, v0
	v_mov_b32_e32 v32, v0
	v_mov_b32_e32 v33, v0
	v_mov_b32_e32 v34, v0
	v_mov_b32_e32 v35, v0
	v_mov_b32_e32 v36, v0
	v_mov_b32_e32 v37, v0
	v_mov_b32_e32 v38, v0
	v_mov_b32_e32 v39, v0
	v_mov_b32_e32 v48, v0
	v_mov_b32_e32 v49, v0
	v_mov_b32_e32 v50, v0
	v_mov_b32_e32 v51, v0
	v_mov_b32_e32 v52, v0
	v_mov_b32_e32 v53, v0
	v_mov_b32_e32 v54, v0
	v_mov_b32_e32 v55, v0
	v_mov_b32_e32 v8, v0
	v_mov_b32_e32 v9, v0
	v_mov_b32_e32 v10, v0
	v_mov_b32_e32 v11, v0
	v_mov_b32_e32 v12, v0
	v_mov_b32_e32 v13, v0
	v_mov_b32_e32 v14, v0
	v_mov_b32_e32 v15, v0
	v_mov_b32_e32 v24, v0
	v_mov_b32_e32 v25, v0
	v_mov_b32_e32 v26, v0
	v_mov_b32_e32 v27, v0
	v_mov_b32_e32 v28, v0
	v_mov_b32_e32 v29, v0
	v_mov_b32_e32 v30, v0
	v_mov_b32_e32 v31, v0
	v_mov_b32_e32 v40, v0
	v_mov_b32_e32 v41, v0
	v_mov_b32_e32 v42, v0
	v_mov_b32_e32 v43, v0
	v_mov_b32_e32 v44, v0
	v_mov_b32_e32 v45, v0
	v_mov_b32_e32 v46, v0
	v_mov_b32_e32 v47, v0
	v_mov_b32_e32 v56, v0
	v_mov_b32_e32 v57, v0
	v_mov_b32_e32 v58, v0
	v_mov_b32_e32 v59, v0
	v_mov_b32_e32 v60, v0
	v_mov_b32_e32 v61, v0
	v_mov_b32_e32 v62, v0
	v_mov_b32_e32 v63, v0
	v_mov_b32_e32 v64, v0
	v_mov_b32_e32 v65, v0
	v_mov_b32_e32 v66, v0
	v_mov_b32_e32 v67, v0
	v_mov_b32_e32 v68, v0
	v_mov_b32_e32 v69, v0
	v_mov_b32_e32 v70, v0
	v_mov_b32_e32 v71, v0
	v_mov_b32_e32 v80, v0
	v_mov_b32_e32 v81, v0
	v_mov_b32_e32 v82, v0
	v_mov_b32_e32 v83, v0
	v_mov_b32_e32 v84, v0
	v_mov_b32_e32 v85, v0
	v_mov_b32_e32 v86, v0
	v_mov_b32_e32 v87, v0
	v_mov_b32_e32 v96, v0
	v_mov_b32_e32 v97, v0
	v_mov_b32_e32 v98, v0
	v_mov_b32_e32 v99, v0
	v_mov_b32_e32 v104, v0
	v_mov_b32_e32 v105, v0
	v_mov_b32_e32 v106, v0
	v_mov_b32_e32 v107, v0
	v_mov_b32_e32 v112, v0
	v_mov_b32_e32 v113, v0
	v_mov_b32_e32 v114, v0
	v_mov_b32_e32 v115, v0
	v_mov_b32_e32 v116, v0
	v_mov_b32_e32 v117, v0
	v_mov_b32_e32 v118, v0
	v_mov_b32_e32 v119, v0
	v_mov_b32_e32 v72, v0
	v_mov_b32_e32 v73, v0
	v_mov_b32_e32 v74, v0
	v_mov_b32_e32 v75, v0
	v_mov_b32_e32 v76, v0
	v_mov_b32_e32 v77, v0
	v_mov_b32_e32 v78, v0
	v_mov_b32_e32 v79, v0
	v_mov_b32_e32 v88, v0
	v_mov_b32_e32 v89, v0
	v_mov_b32_e32 v90, v0
	v_mov_b32_e32 v91, v0
	v_mov_b32_e32 v92, v0
	v_mov_b32_e32 v93, v0
	v_mov_b32_e32 v94, v0
	v_mov_b32_e32 v95, v0
	v_mov_b32_e32 v100, v0
	v_mov_b32_e32 v101, v0
	v_mov_b32_e32 v102, v0
	v_mov_b32_e32 v103, v0
	v_mov_b32_e32 v108, v0
	v_mov_b32_e32 v109, v0
	v_mov_b32_e32 v110, v0
	v_mov_b32_e32 v111, v0
	v_mov_b32_e32 v120, v0
	v_mov_b32_e32 v121, v0
	v_mov_b32_e32 v122, v0
	v_mov_b32_e32 v123, v0
	v_mov_b32_e32 v124, v0
	v_mov_b32_e32 v125, v0
	v_mov_b32_e32 v126, v0
	v_mov_b32_e32 v127, v0
	s_cmp_eq_u64 s[20:21], 0
	s_cbranch_scc0 .Lprio_835
	s_setprio 1
.Lprio_835:
.LBB0_835:
	ds_read_b128 v[128:131], v226
	ds_read_b128 v[158:161], v226 offset:1024
	ds_read_b128 v[162:165], v226 offset:2048
	ds_read_b128 v[166:169], v226 offset:3072
	ds_read_b128 v[170:173], v227
	ds_read_b128 v[174:177], v227 offset:1024
	ds_read_b128 v[178:181], v227 offset:2048
	ds_read_b128 v[182:185], v227 offset:3072
	s_add_u32 s8, s6, 0xfffc0080
	s_addc_u32 s9, s7, -1
	s_cmp_eq_u32 s80, 12
	s_cselect_b32 s79, s5, s9
	s_cselect_b32 s78, s12, s8
	s_cselect_b32 s9, s56, s73
	s_cselect_b32 s8, s57, s71
	v_lshl_add_u64 v[218:219], s[6:7], 0, v[150:151]
	s_add_i32 m0, s30, 0xc000
	ds_read_b128 v[186:189], v228
	ds_read_b128 v[190:193], v228 offset:1024
	ds_read_b128 v[194:197], v228 offset:2048
	ds_read_b128 v[198:201], v228 offset:3072
	ds_read_b128 v[202:205], v228 offset:4096
	ds_read_b128 v[206:209], v228 offset:5120
	ds_read_b128 v[210:213], v228 offset:6144
	ds_read_b128 v[214:217], v228 offset:7168
	global_load_lds_dwordx4 v[218:219], off
	v_lshl_add_u64 v[218:219], s[6:7], 0, v[152:153]
	s_add_i32 m0, s30, 0xe000
	s_nop 0
	global_load_lds_dwordx4 v[218:219], off
	s_waitcnt vmcnt(8)
	s_waitcnt lgkmcnt(0)
	s_barrier
; #define PG8_STAGE(bufoff, gbase, voff) do { _Pragma("unroll") for (int _i = 0; _i < 2; ++_i) \
;         __builtin_amdgcn_global_load_lds((const unsigned*)((const char*)(gbase) + (voff)[_i]), (PG8_LAS unsigned*)(lds + (bufoff) + ldsw + _i * 8192), 16, 0, 0); } while (0)
; #define PG8_LDA(dst, b, h) do { _Pragma("unroll") for (int m = 0; m < 4; ++m) _Pragma("unroll") for (int k = 0; k < 2; ++k) dst[m][k] = *(const PG8_LAS bf16x8*)(lds + PG8_SA(b, h) + aoff + m * 2048 + k * 1024); } while (0)
; #define PG8_LDB(dst, b, h) do { _Pragma("unroll") for (int n = 0; n < 2; ++n) _Pragma("unroll") for (int k = 0; k < 2; ++k) dst[n][k] = *(const PG8_LAS bf16x8*)(lds + PG8_SB(b, h) + boff + n * 2048 + k * 1024); } while (0)
; #define PG8_MMA(ai, bj, At, Bt) do { __builtin_amdgcn_s_setprio(1); _Pragma("unroll") for (int m = 0; m < 4; ++m) _Pragma("unroll") for (int n = 0; n < 2; ++n) _Pragma("unroll") for (int k = 0; k < 2; ++k) \
;         acc[ai][bj][m][n] = __builtin_amdgcn_mfma_f32_16x16x32_bf16(Bt[n][k], At[m][k], acc[ai][bj][m][n], 0, 0, 0); __builtin_amdgcn_s_setprio(0); } while (0)
; #define PG8_WAIT_V(n) asm volatile("s_waitcnt vmcnt(" #n ")" ::: "memory")
; #define PG8_WAIT_L(n) asm volatile("s_waitcnt lgkmcnt(" #n ")" ::: "memory")
; #define PG8_BAR __builtin_amdgcn_s_barrier()
; #define PG8_SCHED __builtin_amdgcn_sched_barrier(0)
; template <class Epi, class Sched, bool ALIGN_EPI = false, bool SP2 = false>
; __device__ __forceinline__ void gemm_phase(PG8_LAS unsigned char* lds, const Gemm g, const Sched& S, const Epi& E) {
;     ...
;             PG8_WAIT_V(8); PG8_WAIT_L(0); PG8_BAR; PG8_MMA(0, 0, At, B0); PG8_MMA(0, 1, At, B1); PG8_BAR; PG8_SCHED;
;             PG8_LDA(At, 0, 1); PG8_STAGE(PG8_SB(0, 0), b2, voffB); PG8_STAGE(PG8_SB(0, 1), b2 + hstep, voffB); PG8_STAGE(PG8_SA(0, 0), a2, voffA);
;             PG8_WAIT_V(8); PG8_WAIT_L(0); PG8_BAR; PG8_MMA(1, 0, At, B0); PG8_MMA(1, 1, At, B1); PG8_BAR; PG8_SCHED;
;             PG8_LDB(B0, 1, 0); PG8_LDB(B1, 1, 1); PG8_SCHED; PG8_LDA(At, 1, 0); PG8_STAGE(PG8_SA(0, 1), a2 + hstep, voffA);
;             PG8_WAIT_V(8); PG8_WAIT_L(0); PG8_BAR; PG8_MMA(0, 0, At, B0); PG8_MMA(0, 1, At, B1); PG8_BAR; PG8_SCHED;
	s_waitcnt lgkmcnt(0)
	v_mfma_f32_16x16x32_bf16 v[124:127], v[128:131], v[186:189], v[124:127]
	v_mfma_f32_16x16x32_bf16 v[120:123], v[162:165], v[186:189], v[120:123]
	v_mfma_f32_16x16x32_bf16 v[108:111], v[128:131], v[194:197], v[108:111]
	v_mfma_f32_16x16x32_bf16 v[100:103], v[162:165], v[194:197], v[100:103]
	v_mfma_f32_16x16x32_bf16 v[92:95], v[128:131], v[202:205], v[92:95]
	v_mfma_f32_16x16x32_bf16 v[88:91], v[162:165], v[202:205], v[88:91]
	v_mfma_f32_16x16x32_bf16 v[76:79], v[128:131], v[210:213], v[76:79]
	v_mfma_f32_16x16x32_bf16 v[72:75], v[162:165], v[210:213], v[72:75]
	v_mfma_f32_16x16x32_bf16 v[124:127], v[158:161], v[190:193], v[124:127]
	v_mfma_f32_16x16x32_bf16 v[120:123], v[166:169], v[190:193], v[120:123]
	v_mfma_f32_16x16x32_bf16 v[108:111], v[158:161], v[198:201], v[108:111]
	v_mfma_f32_16x16x32_bf16 v[100:103], v[166:169], v[198:201], v[100:103]
	v_mfma_f32_16x16x32_bf16 v[92:95], v[158:161], v[206:209], v[92:95]
	v_mfma_f32_16x16x32_bf16 v[88:91], v[166:169], v[206:209], v[88:91]
	v_mfma_f32_16x16x32_bf16 v[76:79], v[158:161], v[214:217], v[76:79]
	v_mfma_f32_16x16x32_bf16 v[72:75], v[166:169], v[214:217], v[72:75]
	v_mfma_f32_16x16x32_bf16 v[116:119], v[170:173], v[186:189], v[116:119]
	v_mfma_f32_16x16x32_bf16 v[112:115], v[178:181], v[186:189], v[112:115]
	v_mfma_f32_16x16x32_bf16 v[104:107], v[170:173], v[194:197], v[104:107]
	v_mfma_f32_16x16x32_bf16 v[96:99], v[178:181], v[194:197], v[96:99]
	v_mfma_f32_16x16x32_bf16 v[84:87], v[170:173], v[202:205], v[84:87]
	v_mfma_f32_16x16x32_bf16 v[80:83], v[178:181], v[202:205], v[80:83]
	v_mfma_f32_16x16x32_bf16 v[68:71], v[170:173], v[210:213], v[68:71]
	v_mfma_f32_16x16x32_bf16 v[64:67], v[178:181], v[210:213], v[64:67]
	v_mfma_f32_16x16x32_bf16 v[116:119], v[174:177], v[190:193], v[116:119]
	v_mfma_f32_16x16x32_bf16 v[112:115], v[182:185], v[190:193], v[112:115]
	v_mfma_f32_16x16x32_bf16 v[104:107], v[174:177], v[198:201], v[104:107]
	v_mfma_f32_16x16x32_bf16 v[96:99], v[182:185], v[198:201], v[96:99]
	v_mfma_f32_16x16x32_bf16 v[84:87], v[174:177], v[206:209], v[84:87]
	v_mfma_f32_16x16x32_bf16 v[80:83], v[182:185], v[206:209], v[80:83]
	v_mfma_f32_16x16x32_bf16 v[68:71], v[174:177], v[214:217], v[68:71]
	v_mfma_f32_16x16x32_bf16 v[64:67], v[182:185], v[214:217], v[64:67]
	s_barrier
	s_add_i32 s81, s89, s22
	v_lshl_add_u64 v[218:219], s[8:9], 0, v[136:137]
	s_mov_b32 m0, s81
	ds_read_b128 v[186:189], v228 offset:16384
	ds_read_b128 v[190:193], v228 offset:17408
	ds_read_b128 v[194:197], v228 offset:18432
	ds_read_b128 v[198:201], v228 offset:19456
	ds_read_b128 v[202:205], v228 offset:20480
	ds_read_b128 v[206:209], v228 offset:21504
	ds_read_b128 v[210:213], v228 offset:22528
	ds_read_b128 v[214:217], v228 offset:23552
	global_load_lds_dwordx4 v[218:219], off
	s_add_i32 m0, s81, 0x2000
	s_add_u32 s82, s8, 0x40000
	v_lshl_add_u64 v[220:221], s[8:9], 0, v[132:133]
	s_addc_u32 s83, s9, 0
	s_add_i32 s81, s90, s22
	global_load_lds_dwordx4 v[220:221], off
	v_lshl_add_u64 v[222:223], s[82:83], 0, v[136:137]
	s_mov_b32 m0, s81
	v_lshl_add_u64 v[230:231], s[78:79], 0, v[134:135]
	global_load_lds_dwordx4 v[222:223], off
	v_lshl_add_u64 v[244:245], s[82:83], 0, v[132:133]
	v_lshl_add_u64 v[222:223], s[78:79], 0, v[138:139]
	s_waitcnt vmcnt(5)
	s_waitcnt lgkmcnt(0)
	s_barrier
	s_waitcnt lgkmcnt(0)
	v_mfma_f32_16x16x32_bf16 v[60:63], v[128:131], v[186:189], v[60:63]
	v_mfma_f32_16x16x32_bf16 v[56:59], v[162:165], v[186:189], v[56:59]
	v_mfma_f32_16x16x32_bf16 v[44:47], v[128:131], v[194:197], v[44:47]
	v_mfma_f32_16x16x32_bf16 v[40:43], v[162:165], v[194:197], v[40:43]
	s_add_i32 m0, s81, 0x2000
	v_mfma_f32_16x16x32_bf16 v[28:31], v[128:131], v[202:205], v[28:31]
	global_load_lds_dwordx4 v[244:245], off
	v_mfma_f32_16x16x32_bf16 v[24:27], v[162:165], v[202:205], v[24:27]
	v_mfma_f32_16x16x32_bf16 v[12:15], v[128:131], v[210:213], v[12:15]
	v_mfma_f32_16x16x32_bf16 v[8:11], v[162:165], v[210:213], v[8:11]
	v_mfma_f32_16x16x32_bf16 v[60:63], v[158:161], v[190:193], v[60:63]
	v_mfma_f32_16x16x32_bf16 v[56:59], v[166:169], v[190:193], v[56:59]
	v_mfma_f32_16x16x32_bf16 v[44:47], v[158:161], v[198:201], v[44:47]
	v_mfma_f32_16x16x32_bf16 v[40:43], v[166:169], v[198:201], v[40:43]
	s_mov_b32 m0, s30
	v_mfma_f32_16x16x32_bf16 v[28:31], v[158:161], v[206:209], v[28:31]
	global_load_lds_dwordx4 v[222:223], off
	v_mfma_f32_16x16x32_bf16 v[24:27], v[166:169], v[206:209], v[24:27]
	v_mfma_f32_16x16x32_bf16 v[12:15], v[158:161], v[214:217], v[12:15]
	v_mfma_f32_16x16x32_bf16 v[8:11], v[166:169], v[214:217], v[8:11]
	v_mfma_f32_16x16x32_bf16 v[52:55], v[170:173], v[186:189], v[52:55]
	v_mfma_f32_16x16x32_bf16 v[48:51], v[178:181], v[186:189], v[48:51]
	v_mfma_f32_16x16x32_bf16 v[36:39], v[170:173], v[194:197], v[36:39]
	v_mfma_f32_16x16x32_bf16 v[32:35], v[178:181], v[194:197], v[32:35]
	s_mov_b32 m0, s31
	v_mfma_f32_16x16x32_bf16 v[20:23], v[170:173], v[202:205], v[20:23]
	global_load_lds_dwordx4 v[230:231], off
	v_mfma_f32_16x16x32_bf16 v[16:19], v[178:181], v[202:205], v[16:19]
	v_mfma_f32_16x16x32_bf16 v[4:7], v[170:173], v[210:213], v[4:7]
	v_mfma_f32_16x16x32_bf16 v[0:3], v[178:181], v[210:213], v[0:3]
	v_mfma_f32_16x16x32_bf16 v[52:55], v[174:177], v[190:193], v[52:55]
	v_mfma_f32_16x16x32_bf16 v[48:51], v[182:185], v[190:193], v[48:51]
	v_mfma_f32_16x16x32_bf16 v[36:39], v[174:177], v[198:201], v[36:39]
	v_mfma_f32_16x16x32_bf16 v[32:35], v[182:185], v[198:201], v[32:35]
	v_mfma_f32_16x16x32_bf16 v[20:23], v[174:177], v[206:209], v[20:23]
	v_mfma_f32_16x16x32_bf16 v[16:19], v[182:185], v[206:209], v[16:19]
	v_mfma_f32_16x16x32_bf16 v[4:7], v[174:177], v[214:217], v[4:7]
	v_mfma_f32_16x16x32_bf16 v[0:3], v[182:185], v[214:217], v[0:3]
	s_barrier
; #define PG8_STAGE(bufoff, gbase, voff) do { _Pragma("unroll") for (int _i = 0; _i < 2; ++_i) \
;         __builtin_amdgcn_global_load_lds((const unsigned*)((const char*)(gbase) + (voff)[_i]), (PG8_LAS unsigned*)(lds + (bufoff) + ldsw + _i * 8192), 16, 0, 0); } while (0)
; #define PG8_LDA(dst, b, h) do { _Pragma("unroll") for (int m = 0; m < 4; ++m) _Pragma("unroll") for (int k = 0; k < 2; ++k) dst[m][k] = *(const PG8_LAS bf16x8*)(lds + PG8_SA(b, h) + aoff + m * 2048 + k * 1024); } while (0)
; #define PG8_LDB(dst, b, h) do { _Pragma("unroll") for (int n = 0; n < 2; ++n) _Pragma("unroll") for (int k = 0; k < 2; ++k) dst[n][k] = *(const PG8_LAS bf16x8*)(lds + PG8_SB(b, h) + boff + n * 2048 + k * 1024); } while (0)
; #define PG8_MMA(ai, bj, At, Bt) do { __builtin_amdgcn_s_setprio(1); _Pragma("unroll") for (int m = 0; m < 4; ++m) _Pragma("unroll") for (int n = 0; n < 2; ++n) _Pragma("unroll") for (int k = 0; k < 2; ++k) \
;         acc[ai][bj][m][n] = __builtin_amdgcn_mfma_f32_16x16x32_bf16(Bt[n][k], At[m][k], acc[ai][bj][m][n], 0, 0, 0); __builtin_amdgcn_s_setprio(0); } while (0)
; #define PG8_WAIT_V(n) asm volatile("s_waitcnt vmcnt(" #n ")" ::: "memory")
; #define PG8_WAIT_L(n) asm volatile("s_waitcnt lgkmcnt(" #n ")" ::: "memory")
; #define PG8_BAR __builtin_amdgcn_s_barrier()
; #define PG8_SCHED __builtin_amdgcn_sched_barrier(0)
; template <class Epi, class Sched, bool ALIGN_EPI = false, bool SP2 = false>
; __device__ __forceinline__ void gemm_phase(PG8_LAS unsigned char* lds, const Gemm g, const Sched& S, const Epi& E) {
;     ...
;             PG8_LDB(B0, 1, 0); PG8_LDB(B1, 1, 1); PG8_SCHED; PG8_LDA(At, 1, 0); PG8_STAGE(PG8_SA(0, 1), a2 + hstep, voffA);
;             PG8_WAIT_V(8); PG8_WAIT_L(0); PG8_BAR; PG8_MMA(0, 0, At, B0); PG8_MMA(0, 1, At, B1); PG8_BAR; PG8_SCHED;
	s_add_i32 s81, 0, 0x18000
	v_add_u32_e32 v140, s81, v225
	s_add_i32 s82, 0, 0x1c000
	ds_read_b128 v[128:131], v140
	ds_read_b128 v[158:161], v140 offset:1024
	ds_read_b128 v[162:165], v140 offset:2048
	ds_read_b128 v[166:169], v140 offset:3072
	v_add_u32_e32 v140, s82, v225
	ds_read_b128 v[170:173], v140
	ds_read_b128 v[174:177], v140 offset:1024
	ds_read_b128 v[178:181], v140 offset:2048
	ds_read_b128 v[182:185], v140 offset:3072
	s_add_u32 s78, s78, 0x40000
	s_addc_u32 s79, s79, 0
	s_mov_b32 m0, s33
	v_lshl_add_u64 v[232:233], s[78:79], 0, v[138:139]
	ds_read_b128 v[186:189], v228 offset:32768
	ds_read_b128 v[190:193], v228 offset:33792
	ds_read_b128 v[194:197], v228 offset:34816
	ds_read_b128 v[198:201], v228 offset:35840
	ds_read_b128 v[202:205], v228 offset:36864
	ds_read_b128 v[206:209], v228 offset:37888
	ds_read_b128 v[210:213], v228 offset:38912
	ds_read_b128 v[214:217], v228 offset:39936
	global_load_lds_dwordx4 v[232:233], off
	v_lshl_add_u64 v[232:233], s[78:79], 0, v[134:135]
	s_mov_b32 m0, s53
	s_nop 0
	global_load_lds_dwordx4 v[232:233], off
	s_waitcnt vmcnt(8)
	s_waitcnt lgkmcnt(0)
	s_barrier
	s_waitcnt lgkmcnt(0)
	v_mfma_f32_16x16x32_bf16 v[124:127], v[128:131], v[186:189], v[124:127]
	v_mfma_f32_16x16x32_bf16 v[120:123], v[162:165], v[186:189], v[120:123]
	v_mfma_f32_16x16x32_bf16 v[108:111], v[128:131], v[194:197], v[108:111]
	v_mfma_f32_16x16x32_bf16 v[100:103], v[162:165], v[194:197], v[100:103]
	v_mfma_f32_16x16x32_bf16 v[92:95], v[128:131], v[202:205], v[92:95]
	v_mfma_f32_16x16x32_bf16 v[88:91], v[162:165], v[202:205], v[88:91]
	v_mfma_f32_16x16x32_bf16 v[76:79], v[128:131], v[210:213], v[76:79]
	v_mfma_f32_16x16x32_bf16 v[72:75], v[162:165], v[210:213], v[72:75]
	v_mfma_f32_16x16x32_bf16 v[124:127], v[158:161], v[190:193], v[124:127]
	v_mfma_f32_16x16x32_bf16 v[120:123], v[166:169], v[190:193], v[120:123]
	v_mfma_f32_16x16x32_bf16 v[108:111], v[158:161], v[198:201], v[108:111]
	v_mfma_f32_16x16x32_bf16 v[100:103], v[166:169], v[198:201], v[100:103]
	v_mfma_f32_16x16x32_bf16 v[92:95], v[158:161], v[206:209], v[92:95]
	v_mfma_f32_16x16x32_bf16 v[88:91], v[166:169], v[206:209], v[88:91]
	v_mfma_f32_16x16x32_bf16 v[76:79], v[158:161], v[214:217], v[76:79]
	v_mfma_f32_16x16x32_bf16 v[72:75], v[166:169], v[214:217], v[72:75]
	v_mfma_f32_16x16x32_bf16 v[116:119], v[170:173], v[186:189], v[116:119]
	v_mfma_f32_16x16x32_bf16 v[112:115], v[178:181], v[186:189], v[112:115]
	v_mfma_f32_16x16x32_bf16 v[104:107], v[170:173], v[194:197], v[104:107]
	v_mfma_f32_16x16x32_bf16 v[96:99], v[178:181], v[194:197], v[96:99]
	v_mfma_f32_16x16x32_bf16 v[84:87], v[170:173], v[202:205], v[84:87]
	v_mfma_f32_16x16x32_bf16 v[80:83], v[178:181], v[202:205], v[80:83]
	v_mfma_f32_16x16x32_bf16 v[68:71], v[170:173], v[210:213], v[68:71]
	v_mfma_f32_16x16x32_bf16 v[64:67], v[178:181], v[210:213], v[64:67]
	v_mfma_f32_16x16x32_bf16 v[116:119], v[174:177], v[190:193], v[116:119]
	v_mfma_f32_16x16x32_bf16 v[112:115], v[182:185], v[190:193], v[112:115]
	v_mfma_f32_16x16x32_bf16 v[104:107], v[174:177], v[198:201], v[104:107]
	v_mfma_f32_16x16x32_bf16 v[96:99], v[182:185], v[198:201], v[96:99]
	v_mfma_f32_16x16x32_bf16 v[84:87], v[174:177], v[206:209], v[84:87]
	v_mfma_f32_16x16x32_bf16 v[80:83], v[182:185], v[206:209], v[80:83]
	v_mfma_f32_16x16x32_bf16 v[68:71], v[174:177], v[214:217], v[68:71]
	v_mfma_f32_16x16x32_bf16 v[64:67], v[182:185], v[214:217], v[64:67]
	s_barrier
; #define PG8_STAGE(bufoff, gbase, voff) do { _Pragma("unroll") for (int _i = 0; _i < 2; ++_i) \
;         __builtin_amdgcn_global_load_lds((const unsigned*)((const char*)(gbase) + (voff)[_i]), (PG8_LAS unsigned*)(lds + (bufoff) + ldsw + _i * 8192), 16, 0, 0); } while (0)
; #define PG8_LDA(dst, b, h) do { _Pragma("unroll") for (int m = 0; m < 4; ++m) _Pragma("unroll") for (int k = 0; k < 2; ++k) dst[m][k] = *(const PG8_LAS bf16x8*)(lds + PG8_SA(b, h) + aoff + m * 2048 + k * 1024); } while (0)
; #define PG8_MMA(ai, bj, At, Bt) do { __builtin_amdgcn_s_setprio(1); _Pragma("unroll") for (int m = 0; m < 4; ++m) _Pragma("unroll") for (int n = 0; n < 2; ++n) _Pragma("unroll") for (int k = 0; k < 2; ++k) \
;         acc[ai][bj][m][n] = __builtin_amdgcn_mfma_f32_16x16x32_bf16(Bt[n][k], At[m][k], acc[ai][bj][m][n], 0, 0, 0); __builtin_amdgcn_s_setprio(0); } while (0)
; #define PG8_WAIT_V(n) asm volatile("s_waitcnt vmcnt(" #n ")" ::: "memory")
; #define PG8_WAIT_L(n) asm volatile("s_waitcnt lgkmcnt(" #n ")" ::: "memory")
; #define PG8_BAR __builtin_amdgcn_s_barrier()
; #define PG8_SCHED __builtin_amdgcn_sched_barrier(0)
; template <class Epi, class Sched, bool ALIGN_EPI = false, bool SP2 = false>
; __device__ __forceinline__ void gemm_phase(PG8_LAS unsigned char* lds, const Gemm g, const Sched& S, const Epi& E) {
;     ...
;             PG8_LDA(At, 1, 1); PG8_STAGE(PG8_SB(1, 0), b3, voffB); PG8_STAGE(PG8_SB(1, 1), b3 + hstep, voffB); PG8_STAGE(PG8_SA(1, 0), a3, voffA);
;             PG8_WAIT_V(8); PG8_WAIT_L(0); PG8_BAR; PG8_MMA(1, 0, At, B0); PG8_MMA(1, 1, At, B1); PG8_BAR; PG8_SCHED;
;     ...
;         if constexpr (ALIGN_EPI) { if (wr == 0) PG8_BAR; }
;         if constexpr (!Epi::AFTER_DRAIN) { E(acc, cur, wr, wc, fr, fq); S.done(cur); }
;         if (!has_next) break;
	s_add_i32 s78, s81, s22
	v_lshl_add_u64 v[218:219], v[218:219], 0, s[18:19]
	s_mov_b32 m0, s78
	ds_read_b128 v[186:189], v228 offset:49152
	ds_read_b128 v[190:193], v228 offset:50176
	ds_read_b128 v[194:197], v228 offset:51200
	ds_read_b128 v[198:201], v228 offset:52224
	ds_read_b128 v[202:205], v228 offset:53248
	ds_read_b128 v[206:209], v228 offset:54272
	ds_read_b128 v[210:213], v228 offset:55296
	ds_read_b128 v[214:217], v228 offset:56320
	global_load_lds_dwordx4 v[218:219], off
	s_add_i32 m0, s78, 0x2000
	s_add_u32 s8, s8, 0x40080
	v_lshl_add_u64 v[218:219], v[220:221], 0, s[18:19]
	s_addc_u32 s9, s9, 0
	s_add_i32 s78, s82, s22
	global_load_lds_dwordx4 v[218:219], off
	v_lshl_add_u64 v[218:219], s[8:9], 0, v[136:137]
	s_mov_b32 m0, s78
	s_nop 0
	global_load_lds_dwordx4 v[218:219], off
	v_lshl_add_u64 v[244:245], s[8:9], 0, v[132:133]
	v_lshl_add_u64 v[246:247], v[222:223], 0, s[18:19]
	v_lshl_add_u64 v[218:219], v[230:231], 0, s[18:19]
	s_waitcnt vmcnt(5)
	s_waitcnt lgkmcnt(0)
	s_barrier
	s_waitcnt lgkmcnt(0)
	v_mfma_f32_16x16x32_bf16 v[60:63], v[128:131], v[186:189], v[60:63]
	v_mfma_f32_16x16x32_bf16 v[56:59], v[162:165], v[186:189], v[56:59]
	v_mfma_f32_16x16x32_bf16 v[44:47], v[128:131], v[194:197], v[44:47]
	v_mfma_f32_16x16x32_bf16 v[40:43], v[162:165], v[194:197], v[40:43]
	s_add_i32 m0, s78, 0x2000
	v_mfma_f32_16x16x32_bf16 v[28:31], v[128:131], v[202:205], v[28:31]
	global_load_lds_dwordx4 v[244:245], off
	v_mfma_f32_16x16x32_bf16 v[24:27], v[162:165], v[202:205], v[24:27]
	v_mfma_f32_16x16x32_bf16 v[12:15], v[128:131], v[210:213], v[12:15]
	v_mfma_f32_16x16x32_bf16 v[8:11], v[162:165], v[210:213], v[8:11]
	v_mfma_f32_16x16x32_bf16 v[60:63], v[158:161], v[190:193], v[60:63]
	v_mfma_f32_16x16x32_bf16 v[56:59], v[166:169], v[190:193], v[56:59]
	v_mfma_f32_16x16x32_bf16 v[44:47], v[158:161], v[198:201], v[44:47]
	v_mfma_f32_16x16x32_bf16 v[40:43], v[166:169], v[198:201], v[40:43]
	s_mov_b32 m0, s61
	v_mfma_f32_16x16x32_bf16 v[28:31], v[158:161], v[206:209], v[28:31]
	global_load_lds_dwordx4 v[246:247], off
	v_mfma_f32_16x16x32_bf16 v[24:27], v[166:169], v[206:209], v[24:27]
	v_mfma_f32_16x16x32_bf16 v[12:15], v[158:161], v[214:217], v[12:15]
	v_mfma_f32_16x16x32_bf16 v[8:11], v[166:169], v[214:217], v[8:11]
	v_mfma_f32_16x16x32_bf16 v[52:55], v[170:173], v[186:189], v[52:55]
	v_mfma_f32_16x16x32_bf16 v[48:51], v[178:181], v[186:189], v[48:51]
	v_mfma_f32_16x16x32_bf16 v[36:39], v[170:173], v[194:197], v[36:39]
	v_mfma_f32_16x16x32_bf16 v[32:35], v[178:181], v[194:197], v[32:35]
	s_mov_b32 m0, s69
	v_mfma_f32_16x16x32_bf16 v[20:23], v[170:173], v[202:205], v[20:23]
	global_load_lds_dwordx4 v[218:219], off
	v_mfma_f32_16x16x32_bf16 v[16:19], v[178:181], v[202:205], v[16:19]
	v_mfma_f32_16x16x32_bf16 v[4:7], v[170:173], v[210:213], v[4:7]
	v_mfma_f32_16x16x32_bf16 v[0:3], v[178:181], v[210:213], v[0:3]
	v_mfma_f32_16x16x32_bf16 v[52:55], v[174:177], v[190:193], v[52:55]
	v_mfma_f32_16x16x32_bf16 v[48:51], v[182:185], v[190:193], v[48:51]
	v_mfma_f32_16x16x32_bf16 v[36:39], v[174:177], v[198:201], v[36:39]
	v_mfma_f32_16x16x32_bf16 v[32:35], v[182:185], v[198:201], v[32:35]
	v_mfma_f32_16x16x32_bf16 v[20:23], v[174:177], v[206:209], v[20:23]
	v_mfma_f32_16x16x32_bf16 v[16:19], v[182:185], v[206:209], v[16:19]
	v_mfma_f32_16x16x32_bf16 v[4:7], v[174:177], v[214:217], v[4:7]
	v_mfma_f32_16x16x32_bf16 v[0:3], v[182:185], v[214:217], v[0:3]
	s_barrier
	s_add_i32 s80, s80, 2
	s_add_u32 s6, s6, 0x100
	s_addc_u32 s7, s7, 0
	s_add_u32 s71, s71, 0x100
	s_addc_u32 s73, s73, 0
	s_cmp_gt_u32 s80, 13
	s_cbranch_scc0 .LBB0_835
	s_setprio 0
	s_and_b64 vcc, exec, s[20:21]
	s_cbranch_vccz .LBB0_838
	s_barrier

; #define PG8_STAGE(bufoff, gbase, voff) do { _Pragma("unroll") for (int _i = 0; _i < 2; ++_i) \
;         __builtin_amdgcn_global_load_lds((const unsigned*)((const char*)(gbase) + (voff)[_i]), (PG8_LAS unsigned*)(lds + (bufoff) + ldsw + _i * 8192), 16, 0, 0); } while (0)
; #define PG8_LDA(dst, b, h) do { _Pragma("unroll") for (int m = 0; m < 4; ++m) _Pragma("unroll") for (int k = 0; k < 2; ++k) dst[m][k] = *(const PG8_LAS bf16x8*)(lds + PG8_SA(b, h) + aoff + m * 2048 + k * 1024); } while (0)
; #define PG8_LDB(dst, b, h) do { _Pragma("unroll") for (int n = 0; n < 2; ++n) _Pragma("unroll") for (int k = 0; k < 2; ++k) dst[n][k] = *(const PG8_LAS bf16x8*)(lds + PG8_SB(b, h) + boff + n * 2048 + k * 1024); } while (0)
; #define PG8_WAIT_V(n) asm volatile("s_waitcnt vmcnt(" #n ")" ::: "memory")
; #define PG8_WAIT_L(n) asm volatile("s_waitcnt lgkmcnt(" #n ")" ::: "memory")
; template <class Epi, class Sched, bool ALIGN_EPI = false, bool SP2 = false>
; __device__ __forceinline__ void gemm_phase(PG8_LAS unsigned char* lds, const Gemm g, const Sched& S, const Epi& E) {
;     ...
;         const bool has_next = S.next(ui + 1, nxt);
;         const char* nA = has_next ? (const char*)g.A + (size_t)nxt.pm * tstep : cA; const char* nB = has_next ? (const char*)g.Bt + (size_t)nxt.pn * tstep : cB;
;         asm volatile(".p2align 6" ::: "memory");
;         for (int t = 0; t < nt; t += 2) {
;             const bool last = (t == nt - 2);
;             const char* a1 = cA + (size_t)(t + 1) * kstep;
;             const char* a2 = last ? nA : cA + (size_t)(t + 2) * kstep; const char* b2 = last ? nB : cB + (size_t)(t + 2) * kstep;
;             const char* a3 = a2 + kstep; const char* b3 = b2 + kstep;
;             if (last && has_next) S.a_ready(nxt);
;             if constexpr (SP2) {
;             PG8_LDB(B0, 0, 0); PG8_LDB(B1, 0, 1); PG8_SCHED; PG8_LDA(At, 0, 0); PG8_STAGE(PG8_SA(1, 1), a1 + hstep, voffA);
;             PG8_WAIT_V(8); PG8_WAIT_L(0); PG8_BAR; PG8_MMA(0, 0, At, B0); PG8_MMA(0, 1, At, B1); PG8_BAR; PG8_SCHED;
;     ...
; #pragma unroll
;         for (int a = 0; a < 2; ++a)
; #pragma unroll
;             for (int b = 0; b < 2; ++b)
; #pragma unroll
;                 for (int m = 0; m < 4; ++m)
; #pragma unroll
;                     for (int n = 0; n < 2; ++n) acc[a][b][m][n] = (f32x4){0.f, 0.f, 0.f, 0.f};
;         cur = nxt; cA = nA; cB = nB; ++ui;
.LBB0_992:
	s_ashr_i32 s21, s20, 31
	s_lshl_b64 s[22:23], s[20:21], 19
	s_add_u32 s22, s26, s22
	s_addc_u32 s23, s27, s23
	s_and_b64 s[30:31], s[0:1], exec
	s_cselect_b32 s21, s23, s37
	s_cselect_b32 s51, s22, s36
	s_ashr_i32 s19, s18, 31
	s_lshl_b64 s[30:31], s[18:19], 19
	s_add_u32 s30, s28, s30
	s_addc_u32 s31, s29, s31
	s_and_b64 s[40:41], s[0:1], exec
	s_cselect_b32 s19, s31, s39
	s_cselect_b32 s52, s30, s38
	s_add_u32 s36, s36, 0x40080
	.p2align 6
	s_addc_u32 s37, s37, 0
	s_add_u32 s53, s38, 0x100
	v_mov_b32_e32 v0, 0
	s_addc_u32 s56, s39, 0
	s_mov_b32 s57, -2
	v_mov_b32_e32 v1, v0
	v_mov_b32_e32 v2, v0
	v_mov_b32_e32 v3, v0
	v_mov_b32_e32 v4, v0
	v_mov_b32_e32 v5, v0
	v_mov_b32_e32 v6, v0
	v_mov_b32_e32 v7, v0
	v_mov_b32_e32 v8, v0
	v_mov_b32_e32 v9, v0
	v_mov_b32_e32 v10, v0
	v_mov_b32_e32 v11, v0
	v_mov_b32_e32 v16, v0
	v_mov_b32_e32 v17, v0
	v_mov_b32_e32 v18, v0
	v_mov_b32_e32 v19, v0
	v_mov_b32_e32 v24, v0
	v_mov_b32_e32 v25, v0
	v_mov_b32_e32 v26, v0
	v_mov_b32_e32 v27, v0
	v_mov_b32_e32 v32, v0
	v_mov_b32_e32 v33, v0
	v_mov_b32_e32 v34, v0
	v_mov_b32_e32 v35, v0
	v_mov_b32_e32 v40, v0
	v_mov_b32_e32 v41, v0
	v_mov_b32_e32 v42, v0
	v_mov_b32_e32 v43, v0
	v_mov_b32_e32 v48, v0
	v_mov_b32_e32 v49, v0
	v_mov_b32_e32 v50, v0
	v_mov_b32_e32 v51, v0
	v_mov_b32_e32 v12, v0
	v_mov_b32_e32 v13, v0
	v_mov_b32_e32 v14, v0
	v_mov_b32_e32 v15, v0
	v_mov_b32_e32 v20, v0
	v_mov_b32_e32 v21, v0
	v_mov_b32_e32 v22, v0
	v_mov_b32_e32 v23, v0
	v_mov_b32_e32 v28, v0
	v_mov_b32_e32 v29, v0
	v_mov_b32_e32 v30, v0
	v_mov_b32_e32 v31, v0
	v_mov_b32_e32 v36, v0
	v_mov_b32_e32 v37, v0
	v_mov_b32_e32 v38, v0
	v_mov_b32_e32 v39, v0
	v_mov_b32_e32 v44, v0
	v_mov_b32_e32 v45, v0
	v_mov_b32_e32 v46, v0
	v_mov_b32_e32 v47, v0
	v_mov_b32_e32 v52, v0
	v_mov_b32_e32 v53, v0
	v_mov_b32_e32 v54, v0
	v_mov_b32_e32 v55, v0
	v_mov_b32_e32 v56, v0
	v_mov_b32_e32 v57, v0
	v_mov_b32_e32 v58, v0
	v_mov_b32_e32 v59, v0
	v_mov_b32_e32 v60, v0
	v_mov_b32_e32 v61, v0
	v_mov_b32_e32 v62, v0
	v_mov_b32_e32 v63, v0
	v_mov_b32_e32 v64, v0
	v_mov_b32_e32 v65, v0
	v_mov_b32_e32 v66, v0
	v_mov_b32_e32 v67, v0
	v_mov_b32_e32 v68, v0
	v_mov_b32_e32 v69, v0
	v_mov_b32_e32 v70, v0
	v_mov_b32_e32 v71, v0
	v_mov_b32_e32 v72, v0
	v_mov_b32_e32 v73, v0
	v_mov_b32_e32 v74, v0
	v_mov_b32_e32 v75, v0
	v_mov_b32_e32 v80, v0
	v_mov_b32_e32 v81, v0
	v_mov_b32_e32 v82, v0
	v_mov_b32_e32 v83, v0
	v_mov_b32_e32 v88, v0
	v_mov_b32_e32 v89, v0
	v_mov_b32_e32 v90, v0
	v_mov_b32_e32 v91, v0
	v_mov_b32_e32 v96, v0
	v_mov_b32_e32 v97, v0
	v_mov_b32_e32 v98, v0
	v_mov_b32_e32 v99, v0
	v_mov_b32_e32 v104, v0
	v_mov_b32_e32 v105, v0
	v_mov_b32_e32 v106, v0
	v_mov_b32_e32 v107, v0
	v_mov_b32_e32 v112, v0
	v_mov_b32_e32 v113, v0
	v_mov_b32_e32 v114, v0
	v_mov_b32_e32 v115, v0
	v_mov_b32_e32 v76, v0
	v_mov_b32_e32 v77, v0
	v_mov_b32_e32 v78, v0
	v_mov_b32_e32 v79, v0
	v_mov_b32_e32 v84, v0
	v_mov_b32_e32 v85, v0
	v_mov_b32_e32 v86, v0
	v_mov_b32_e32 v87, v0
	v_mov_b32_e32 v92, v0
	v_mov_b32_e32 v93, v0
	v_mov_b32_e32 v94, v0
	v_mov_b32_e32 v95, v0
	v_mov_b32_e32 v100, v0
	v_mov_b32_e32 v101, v0
	v_mov_b32_e32 v102, v0
	v_mov_b32_e32 v103, v0
	v_mov_b32_e32 v108, v0
	v_mov_b32_e32 v109, v0
	v_mov_b32_e32 v110, v0
	v_mov_b32_e32 v111, v0
	v_mov_b32_e32 v116, v0
	v_mov_b32_e32 v117, v0
	v_mov_b32_e32 v118, v0
	v_mov_b32_e32 v119, v0
	v_mov_b32_e32 v120, v0
	v_mov_b32_e32 v121, v0
	v_mov_b32_e32 v122, v0
	v_mov_b32_e32 v123, v0
	v_mov_b32_e32 v124, v0
	v_mov_b32_e32 v125, v0
	v_mov_b32_e32 v126, v0
	v_mov_b32_e32 v127, v0
	s_cmp_eq_u64 s[8:9], 0
	s_cbranch_scc0 .Lprio_993
	s_setprio 1
.Lprio_993:
.LBB0_993:
	ds_read_b128 v[152:155], v149
	ds_read_b128 v[156:159], v149 offset:1024
	ds_read_b128 v[160:163], v149 offset:2048
	ds_read_b128 v[164:167], v149 offset:3072
	ds_read_b128 v[168:171], v150
	ds_read_b128 v[172:175], v150 offset:1024
	ds_read_b128 v[176:179], v150 offset:2048
	ds_read_b128 v[180:183], v150 offset:3072
	s_add_u32 s38, s36, 0xfffc0080
	s_addc_u32 s39, s37, -1
	s_cmp_eq_u32 s57, 12
	s_cselect_b32 s41, s21, s39
	s_cselect_b32 s40, s51, s38
	s_cselect_b32 s39, s19, s56
	s_cselect_b32 s38, s52, s53
	v_lshl_add_u64 v[144:145], s[36:37], 0, v[136:137]
	s_add_i32 m0, s25, 0xc000
	ds_read_b128 v[184:187], v151
	ds_read_b128 v[188:191], v151 offset:1024
	ds_read_b128 v[192:195], v151 offset:2048
	ds_read_b128 v[196:199], v151 offset:3072
	ds_read_b128 v[200:203], v151 offset:4096
	ds_read_b128 v[204:207], v151 offset:5120
	ds_read_b128 v[208:211], v151 offset:6144
	ds_read_b128 v[212:215], v151 offset:7168
	global_load_lds_dwordx4 v[144:145], off
	v_lshl_add_u64 v[144:145], s[36:37], 0, v[138:139]
	s_add_i32 m0, s25, 0xe000
	s_nop 0
	global_load_lds_dwordx4 v[144:145], off
	s_waitcnt vmcnt(8)
	s_waitcnt lgkmcnt(0)
	s_barrier
; #define PG8_STAGE(bufoff, gbase, voff) do { _Pragma("unroll") for (int _i = 0; _i < 2; ++_i) \
;         __builtin_amdgcn_global_load_lds((const unsigned*)((const char*)(gbase) + (voff)[_i]), (PG8_LAS unsigned*)(lds + (bufoff) + ldsw + _i * 8192), 16, 0, 0); } while (0)
; #define PG8_LDA(dst, b, h) do { _Pragma("unroll") for (int m = 0; m < 4; ++m) _Pragma("unroll") for (int k = 0; k < 2; ++k) dst[m][k] = *(const PG8_LAS bf16x8*)(lds + PG8_SA(b, h) + aoff + m * 2048 + k * 1024); } while (0)
; #define PG8_LDB(dst, b, h) do { _Pragma("unroll") for (int n = 0; n < 2; ++n) _Pragma("unroll") for (int k = 0; k < 2; ++k) dst[n][k] = *(const PG8_LAS bf16x8*)(lds + PG8_SB(b, h) + boff + n * 2048 + k * 1024); } while (0)
; #define PG8_MMA(ai, bj, At, Bt) do { __builtin_amdgcn_s_setprio(1); _Pragma("unroll") for (int m = 0; m < 4; ++m) _Pragma("unroll") for (int n = 0; n < 2; ++n) _Pragma("unroll") for (int k = 0; k < 2; ++k) \
;         acc[ai][bj][m][n] = __builtin_amdgcn_mfma_f32_16x16x32_bf16(Bt[n][k], At[m][k], acc[ai][bj][m][n], 0, 0, 0); __builtin_amdgcn_s_setprio(0); } while (0)
; #define PG8_WAIT_V(n) asm volatile("s_waitcnt vmcnt(" #n ")" ::: "memory")
; #define PG8_WAIT_L(n) asm volatile("s_waitcnt lgkmcnt(" #n ")" ::: "memory")
; #define PG8_BAR __builtin_amdgcn_s_barrier()
; #define PG8_SCHED __builtin_amdgcn_sched_barrier(0)
; template <class Epi, class Sched, bool ALIGN_EPI = false, bool SP2 = false>
; __device__ __forceinline__ void gemm_phase(PG8_LAS unsigned char* lds, const Gemm g, const Sched& S, const Epi& E) {
;     ...
;             PG8_WAIT_V(8); PG8_WAIT_L(0); PG8_BAR; PG8_MMA(0, 0, At, B0); PG8_MMA(0, 1, At, B1); PG8_BAR; PG8_SCHED;
;             PG8_LDA(At, 0, 1); PG8_STAGE(PG8_SB(0, 0), b2, voffB); PG8_STAGE(PG8_SB(0, 1), b2 + hstep, voffB); PG8_STAGE(PG8_SA(0, 0), a2, voffA);
;             PG8_WAIT_V(8); PG8_WAIT_L(0); PG8_BAR; PG8_MMA(1, 0, At, B0); PG8_MMA(1, 1, At, B1); PG8_BAR; PG8_SCHED;
;             PG8_LDB(B0, 1, 0); PG8_LDB(B1, 1, 1); PG8_SCHED; PG8_LDA(At, 1, 0); PG8_STAGE(PG8_SA(0, 1), a2 + hstep, voffA);
;             PG8_WAIT_V(8); PG8_WAIT_L(0); PG8_BAR; PG8_MMA(0, 0, At, B0); PG8_MMA(0, 1, At, B1); PG8_BAR; PG8_SCHED;
	s_waitcnt lgkmcnt(0)
	v_mfma_f32_16x16x32_bf16 v[124:127], v[152:155], v[184:187], v[124:127]
	v_mfma_f32_16x16x32_bf16 v[120:123], v[160:163], v[184:187], v[120:123]
	v_mfma_f32_16x16x32_bf16 v[116:119], v[152:155], v[192:195], v[116:119]
	v_mfma_f32_16x16x32_bf16 v[108:111], v[160:163], v[192:195], v[108:111]
	v_mfma_f32_16x16x32_bf16 v[100:103], v[152:155], v[200:203], v[100:103]
	v_mfma_f32_16x16x32_bf16 v[92:95], v[160:163], v[200:203], v[92:95]
	v_mfma_f32_16x16x32_bf16 v[84:87], v[152:155], v[208:211], v[84:87]
	v_mfma_f32_16x16x32_bf16 v[76:79], v[160:163], v[208:211], v[76:79]
	v_mfma_f32_16x16x32_bf16 v[124:127], v[156:159], v[188:191], v[124:127]
	v_mfma_f32_16x16x32_bf16 v[120:123], v[164:167], v[188:191], v[120:123]
	v_mfma_f32_16x16x32_bf16 v[116:119], v[156:159], v[196:199], v[116:119]
	v_mfma_f32_16x16x32_bf16 v[108:111], v[164:167], v[196:199], v[108:111]
	v_mfma_f32_16x16x32_bf16 v[100:103], v[156:159], v[204:207], v[100:103]
	v_mfma_f32_16x16x32_bf16 v[92:95], v[164:167], v[204:207], v[92:95]
	v_mfma_f32_16x16x32_bf16 v[84:87], v[156:159], v[212:215], v[84:87]
	v_mfma_f32_16x16x32_bf16 v[76:79], v[164:167], v[212:215], v[76:79]
	v_mfma_f32_16x16x32_bf16 v[112:115], v[168:171], v[184:187], v[112:115]
	v_mfma_f32_16x16x32_bf16 v[104:107], v[176:179], v[184:187], v[104:107]
	v_mfma_f32_16x16x32_bf16 v[96:99], v[168:171], v[192:195], v[96:99]
	v_mfma_f32_16x16x32_bf16 v[88:91], v[176:179], v[192:195], v[88:91]
	v_mfma_f32_16x16x32_bf16 v[80:83], v[168:171], v[200:203], v[80:83]
	v_mfma_f32_16x16x32_bf16 v[72:75], v[176:179], v[200:203], v[72:75]
	v_mfma_f32_16x16x32_bf16 v[68:71], v[168:171], v[208:211], v[68:71]
	v_mfma_f32_16x16x32_bf16 v[64:67], v[176:179], v[208:211], v[64:67]
	v_mfma_f32_16x16x32_bf16 v[112:115], v[172:175], v[188:191], v[112:115]
	v_mfma_f32_16x16x32_bf16 v[104:107], v[180:183], v[188:191], v[104:107]
	v_mfma_f32_16x16x32_bf16 v[96:99], v[172:175], v[196:199], v[96:99]
	v_mfma_f32_16x16x32_bf16 v[88:91], v[180:183], v[196:199], v[88:91]
	v_mfma_f32_16x16x32_bf16 v[80:83], v[172:175], v[204:207], v[80:83]
	v_mfma_f32_16x16x32_bf16 v[72:75], v[180:183], v[204:207], v[72:75]
	v_mfma_f32_16x16x32_bf16 v[68:71], v[172:175], v[212:215], v[68:71]
	v_mfma_f32_16x16x32_bf16 v[64:67], v[180:183], v[212:215], v[64:67]
	s_barrier
	s_add_i32 s58, s46, s2
	v_lshl_add_u64 v[144:145], s[38:39], 0, v[132:133]
	s_mov_b32 m0, s58
	ds_read_b128 v[184:187], v151 offset:16384
	ds_read_b128 v[188:191], v151 offset:17408
	ds_read_b128 v[192:195], v151 offset:18432
	ds_read_b128 v[196:199], v151 offset:19456
	ds_read_b128 v[200:203], v151 offset:20480
	ds_read_b128 v[204:207], v151 offset:21504
	ds_read_b128 v[208:211], v151 offset:22528
	ds_read_b128 v[212:215], v151 offset:23552
	global_load_lds_dwordx4 v[144:145], off
	s_add_i32 m0, s58, 0x2000
	s_add_u32 s58, s38, 0x40000
	v_lshl_add_u64 v[216:217], s[38:39], 0, v[128:129]
	s_addc_u32 s59, s39, 0
	s_add_i32 s60, s47, s2
	global_load_lds_dwordx4 v[216:217], off
	v_lshl_add_u64 v[218:219], s[58:59], 0, v[132:133]
	s_mov_b32 m0, s60
	v_lshl_add_u64 v[220:221], s[40:41], 0, v[130:131]
	global_load_lds_dwordx4 v[218:219], off
	v_lshl_add_u64 v[244:245], s[58:59], 0, v[128:129]
	v_lshl_add_u64 v[218:219], s[40:41], 0, v[134:135]
	s_waitcnt vmcnt(5)
	s_waitcnt lgkmcnt(0)
	s_barrier
	s_waitcnt lgkmcnt(0)
	v_mfma_f32_16x16x32_bf16 v[60:63], v[152:155], v[184:187], v[60:63]
	v_mfma_f32_16x16x32_bf16 v[56:59], v[160:163], v[184:187], v[56:59]
	v_mfma_f32_16x16x32_bf16 v[52:55], v[152:155], v[192:195], v[52:55]
	v_mfma_f32_16x16x32_bf16 v[44:47], v[160:163], v[192:195], v[44:47]
	s_add_i32 m0, s60, 0x2000
	v_mfma_f32_16x16x32_bf16 v[36:39], v[152:155], v[200:203], v[36:39]
	global_load_lds_dwordx4 v[244:245], off
	v_mfma_f32_16x16x32_bf16 v[28:31], v[160:163], v[200:203], v[28:31]
	v_mfma_f32_16x16x32_bf16 v[20:23], v[152:155], v[208:211], v[20:23]
	v_mfma_f32_16x16x32_bf16 v[12:15], v[160:163], v[208:211], v[12:15]
	v_mfma_f32_16x16x32_bf16 v[60:63], v[156:159], v[188:191], v[60:63]
	v_mfma_f32_16x16x32_bf16 v[56:59], v[164:167], v[188:191], v[56:59]
	v_mfma_f32_16x16x32_bf16 v[52:55], v[156:159], v[196:199], v[52:55]
	v_mfma_f32_16x16x32_bf16 v[44:47], v[164:167], v[196:199], v[44:47]
	s_mov_b32 m0, s25
	v_mfma_f32_16x16x32_bf16 v[36:39], v[156:159], v[204:207], v[36:39]
	global_load_lds_dwordx4 v[218:219], off
	v_mfma_f32_16x16x32_bf16 v[28:31], v[164:167], v[204:207], v[28:31]
	v_mfma_f32_16x16x32_bf16 v[20:23], v[156:159], v[212:215], v[20:23]
	v_mfma_f32_16x16x32_bf16 v[12:15], v[164:167], v[212:215], v[12:15]
	v_mfma_f32_16x16x32_bf16 v[48:51], v[168:171], v[184:187], v[48:51]
	v_mfma_f32_16x16x32_bf16 v[40:43], v[176:179], v[184:187], v[40:43]
	v_mfma_f32_16x16x32_bf16 v[32:35], v[168:171], v[192:195], v[32:35]
	v_mfma_f32_16x16x32_bf16 v[24:27], v[176:179], v[192:195], v[24:27]
	s_mov_b32 m0, s33
	v_mfma_f32_16x16x32_bf16 v[16:19], v[168:171], v[200:203], v[16:19]
	global_load_lds_dwordx4 v[220:221], off
	v_mfma_f32_16x16x32_bf16 v[8:11], v[176:179], v[200:203], v[8:11]
	v_mfma_f32_16x16x32_bf16 v[4:7], v[168:171], v[208:211], v[4:7]
	v_mfma_f32_16x16x32_bf16 v[0:3], v[176:179], v[208:211], v[0:3]
	v_mfma_f32_16x16x32_bf16 v[48:51], v[172:175], v[188:191], v[48:51]
	v_mfma_f32_16x16x32_bf16 v[40:43], v[180:183], v[188:191], v[40:43]
	v_mfma_f32_16x16x32_bf16 v[32:35], v[172:175], v[196:199], v[32:35]
	v_mfma_f32_16x16x32_bf16 v[24:27], v[180:183], v[196:199], v[24:27]
	v_mfma_f32_16x16x32_bf16 v[16:19], v[172:175], v[204:207], v[16:19]
	v_mfma_f32_16x16x32_bf16 v[8:11], v[180:183], v[204:207], v[8:11]
	v_mfma_f32_16x16x32_bf16 v[4:7], v[172:175], v[212:215], v[4:7]
	v_mfma_f32_16x16x32_bf16 v[0:3], v[180:183], v[212:215], v[0:3]
	s_barrier
; #define PG8_STAGE(bufoff, gbase, voff) do { _Pragma("unroll") for (int _i = 0; _i < 2; ++_i) \
;         __builtin_amdgcn_global_load_lds((const unsigned*)((const char*)(gbase) + (voff)[_i]), (PG8_LAS unsigned*)(lds + (bufoff) + ldsw + _i * 8192), 16, 0, 0); } while (0)
; #define PG8_LDA(dst, b, h) do { _Pragma("unroll") for (int m = 0; m < 4; ++m) _Pragma("unroll") for (int k = 0; k < 2; ++k) dst[m][k] = *(const PG8_LAS bf16x8*)(lds + PG8_SA(b, h) + aoff + m * 2048 + k * 1024); } while (0)
; #define PG8_LDB(dst, b, h) do { _Pragma("unroll") for (int n = 0; n < 2; ++n) _Pragma("unroll") for (int k = 0; k < 2; ++k) dst[n][k] = *(const PG8_LAS bf16x8*)(lds + PG8_SB(b, h) + boff + n * 2048 + k * 1024); } while (0)
; #define PG8_MMA(ai, bj, At, Bt) do { __builtin_amdgcn_s_setprio(1); _Pragma("unroll") for (int m = 0; m < 4; ++m) _Pragma("unroll") for (int n = 0; n < 2; ++n) _Pragma("unroll") for (int k = 0; k < 2; ++k) \
;         acc[ai][bj][m][n] = __builtin_amdgcn_mfma_f32_16x16x32_bf16(Bt[n][k], At[m][k], acc[ai][bj][m][n], 0, 0, 0); __builtin_amdgcn_s_setprio(0); } while (0)
; #define PG8_WAIT_V(n) asm volatile("s_waitcnt vmcnt(" #n ")" ::: "memory")
; #define PG8_WAIT_L(n) asm volatile("s_waitcnt lgkmcnt(" #n ")" ::: "memory")
; #define PG8_BAR __builtin_amdgcn_s_barrier()
; #define PG8_SCHED __builtin_amdgcn_sched_barrier(0)
; template <class Epi, class Sched, bool ALIGN_EPI = false, bool SP2 = false>
; __device__ __forceinline__ void gemm_phase(PG8_LAS unsigned char* lds, const Gemm g, const Sched& S, const Epi& E) {
;     ...
;             PG8_LDB(B0, 1, 0); PG8_LDB(B1, 1, 1); PG8_SCHED; PG8_LDA(At, 1, 0); PG8_STAGE(PG8_SA(0, 1), a2 + hstep, voffA);
;             PG8_WAIT_V(8); PG8_WAIT_L(0); PG8_BAR; PG8_MMA(0, 0, At, B0); PG8_MMA(0, 1, At, B1); PG8_BAR; PG8_SCHED;
	s_add_i32 s58, 0, 0x18000
	s_add_i32 s59, 0, 0x1c000
	v_add_u32_e32 v164, s58, v147
	v_add_u32_e32 v180, s59, v147
	ds_read_b128 v[152:155], v164
	ds_read_b128 v[156:159], v164 offset:1024
	ds_read_b128 v[160:163], v164 offset:2048
	ds_read_b128 v[164:167], v164 offset:3072
	ds_read_b128 v[168:171], v180
	ds_read_b128 v[172:175], v180 offset:1024
	ds_read_b128 v[176:179], v180 offset:2048
	ds_read_b128 v[180:183], v180 offset:3072
	s_add_u32 s40, s40, 0x40000
	s_addc_u32 s41, s41, 0
	s_mov_b32 m0, s35
	v_lshl_add_u64 v[222:223], s[40:41], 0, v[134:135]
	ds_read_b128 v[184:187], v151 offset:32768
	ds_read_b128 v[188:191], v151 offset:33792
	ds_read_b128 v[192:195], v151 offset:34816
	ds_read_b128 v[196:199], v151 offset:35840
	ds_read_b128 v[200:203], v151 offset:36864
	ds_read_b128 v[204:207], v151 offset:37888
	ds_read_b128 v[208:211], v151 offset:38912
	ds_read_b128 v[212:215], v151 offset:39936
	global_load_lds_dwordx4 v[222:223], off
	v_lshl_add_u64 v[222:223], s[40:41], 0, v[130:131]
	s_mov_b32 m0, s42
	s_nop 0
	global_load_lds_dwordx4 v[222:223], off
	s_waitcnt vmcnt(8)
	s_waitcnt lgkmcnt(0)
	s_barrier
	s_waitcnt lgkmcnt(0)
	v_mfma_f32_16x16x32_bf16 v[124:127], v[152:155], v[184:187], v[124:127]
	v_mfma_f32_16x16x32_bf16 v[120:123], v[160:163], v[184:187], v[120:123]
	v_mfma_f32_16x16x32_bf16 v[116:119], v[152:155], v[192:195], v[116:119]
	v_mfma_f32_16x16x32_bf16 v[108:111], v[160:163], v[192:195], v[108:111]
	v_mfma_f32_16x16x32_bf16 v[100:103], v[152:155], v[200:203], v[100:103]
	v_mfma_f32_16x16x32_bf16 v[92:95], v[160:163], v[200:203], v[92:95]
	v_mfma_f32_16x16x32_bf16 v[84:87], v[152:155], v[208:211], v[84:87]
	v_mfma_f32_16x16x32_bf16 v[76:79], v[160:163], v[208:211], v[76:79]
	v_mfma_f32_16x16x32_bf16 v[124:127], v[156:159], v[188:191], v[124:127]
	v_mfma_f32_16x16x32_bf16 v[120:123], v[164:167], v[188:191], v[120:123]
	v_mfma_f32_16x16x32_bf16 v[116:119], v[156:159], v[196:199], v[116:119]
	v_mfma_f32_16x16x32_bf16 v[108:111], v[164:167], v[196:199], v[108:111]
	v_mfma_f32_16x16x32_bf16 v[100:103], v[156:159], v[204:207], v[100:103]
	v_mfma_f32_16x16x32_bf16 v[92:95], v[164:167], v[204:207], v[92:95]
	v_mfma_f32_16x16x32_bf16 v[84:87], v[156:159], v[212:215], v[84:87]
	v_mfma_f32_16x16x32_bf16 v[76:79], v[164:167], v[212:215], v[76:79]
	v_mfma_f32_16x16x32_bf16 v[112:115], v[168:171], v[184:187], v[112:115]
	v_mfma_f32_16x16x32_bf16 v[104:107], v[176:179], v[184:187], v[104:107]
	v_mfma_f32_16x16x32_bf16 v[96:99], v[168:171], v[192:195], v[96:99]
	v_mfma_f32_16x16x32_bf16 v[88:91], v[176:179], v[192:195], v[88:91]
	v_mfma_f32_16x16x32_bf16 v[80:83], v[168:171], v[200:203], v[80:83]
	v_mfma_f32_16x16x32_bf16 v[72:75], v[176:179], v[200:203], v[72:75]
	v_mfma_f32_16x16x32_bf16 v[68:71], v[168:171], v[208:211], v[68:71]
	v_mfma_f32_16x16x32_bf16 v[64:67], v[176:179], v[208:211], v[64:67]
	v_mfma_f32_16x16x32_bf16 v[112:115], v[172:175], v[188:191], v[112:115]
	v_mfma_f32_16x16x32_bf16 v[104:107], v[180:183], v[188:191], v[104:107]
	v_mfma_f32_16x16x32_bf16 v[96:99], v[172:175], v[196:199], v[96:99]
	v_mfma_f32_16x16x32_bf16 v[88:91], v[180:183], v[196:199], v[88:91]
	v_mfma_f32_16x16x32_bf16 v[80:83], v[172:175], v[204:207], v[80:83]
	v_mfma_f32_16x16x32_bf16 v[72:75], v[180:183], v[204:207], v[72:75]
	v_mfma_f32_16x16x32_bf16 v[68:71], v[172:175], v[212:215], v[68:71]
	v_mfma_f32_16x16x32_bf16 v[64:67], v[180:183], v[212:215], v[64:67]
	s_barrier
; #define PG8_STAGE(bufoff, gbase, voff) do { _Pragma("unroll") for (int _i = 0; _i < 2; ++_i) \
;         __builtin_amdgcn_global_load_lds((const unsigned*)((const char*)(gbase) + (voff)[_i]), (PG8_LAS unsigned*)(lds + (bufoff) + ldsw + _i * 8192), 16, 0, 0); } while (0)
; #define PG8_LDA(dst, b, h) do { _Pragma("unroll") for (int m = 0; m < 4; ++m) _Pragma("unroll") for (int k = 0; k < 2; ++k) dst[m][k] = *(const PG8_LAS bf16x8*)(lds + PG8_SA(b, h) + aoff + m * 2048 + k * 1024); } while (0)
; #define PG8_MMA(ai, bj, At, Bt) do { __builtin_amdgcn_s_setprio(1); _Pragma("unroll") for (int m = 0; m < 4; ++m) _Pragma("unroll") for (int n = 0; n < 2; ++n) _Pragma("unroll") for (int k = 0; k < 2; ++k) \
;         acc[ai][bj][m][n] = __builtin_amdgcn_mfma_f32_16x16x32_bf16(Bt[n][k], At[m][k], acc[ai][bj][m][n], 0, 0, 0); __builtin_amdgcn_s_setprio(0); } while (0)
; #define PG8_WAIT_V(n) asm volatile("s_waitcnt vmcnt(" #n ")" ::: "memory")
; #define PG8_WAIT_L(n) asm volatile("s_waitcnt lgkmcnt(" #n ")" ::: "memory")
; #define PG8_BAR __builtin_amdgcn_s_barrier()
; #define PG8_SCHED __builtin_amdgcn_sched_barrier(0)
; template <class Epi, class Sched, bool ALIGN_EPI = false, bool SP2 = false>
; __device__ __forceinline__ void gemm_phase(PG8_LAS unsigned char* lds, const Gemm g, const Sched& S, const Epi& E) {
;     ...
;             PG8_LDA(At, 1, 1); PG8_STAGE(PG8_SB(1, 0), b3, voffB); PG8_STAGE(PG8_SB(1, 1), b3 + hstep, voffB); PG8_STAGE(PG8_SA(1, 0), a3, voffA);
;             PG8_WAIT_V(8); PG8_WAIT_L(0); PG8_BAR; PG8_MMA(1, 0, At, B0); PG8_MMA(1, 1, At, B1); PG8_BAR; PG8_SCHED;
;     ...
;         if constexpr (ALIGN_EPI) { if (wr == 0) PG8_BAR; }
;         if constexpr (!Epi::AFTER_DRAIN) { E(acc, cur, wr, wc, fr, fq); S.done(cur); }
;         if (!has_next) break;
	s_add_i32 s40, s58, s2
	v_lshl_add_u64 v[144:145], v[144:145], 0, s[6:7]
	s_mov_b32 m0, s40
	ds_read_b128 v[184:187], v151 offset:49152
	ds_read_b128 v[188:191], v151 offset:50176
	ds_read_b128 v[192:195], v151 offset:51200
	ds_read_b128 v[196:199], v151 offset:52224
	ds_read_b128 v[200:203], v151 offset:53248
	ds_read_b128 v[204:207], v151 offset:54272
	ds_read_b128 v[208:211], v151 offset:55296
	ds_read_b128 v[212:215], v151 offset:56320
	global_load_lds_dwordx4 v[144:145], off
	s_add_i32 m0, s40, 0x2000
	s_add_u32 s38, s38, 0x40080
	v_lshl_add_u64 v[144:145], v[216:217], 0, s[6:7]
	s_addc_u32 s39, s39, 0
	s_add_i32 s40, s59, s2
	global_load_lds_dwordx4 v[144:145], off
	v_lshl_add_u64 v[144:145], s[38:39], 0, v[132:133]
	s_mov_b32 m0, s40
	s_nop 0
	global_load_lds_dwordx4 v[144:145], off
	v_lshl_add_u64 v[244:245], s[38:39], 0, v[128:129]
	v_lshl_add_u64 v[246:247], v[218:219], 0, s[6:7]
	v_lshl_add_u64 v[144:145], v[220:221], 0, s[6:7]
	s_waitcnt vmcnt(5)
	s_waitcnt lgkmcnt(0)
	s_barrier
	s_waitcnt lgkmcnt(0)
	v_mfma_f32_16x16x32_bf16 v[60:63], v[152:155], v[184:187], v[60:63]
	v_mfma_f32_16x16x32_bf16 v[56:59], v[160:163], v[184:187], v[56:59]
	v_mfma_f32_16x16x32_bf16 v[52:55], v[152:155], v[192:195], v[52:55]
	v_mfma_f32_16x16x32_bf16 v[44:47], v[160:163], v[192:195], v[44:47]
	s_add_i32 m0, s40, 0x2000
	v_mfma_f32_16x16x32_bf16 v[36:39], v[152:155], v[200:203], v[36:39]
	global_load_lds_dwordx4 v[244:245], off
	v_mfma_f32_16x16x32_bf16 v[28:31], v[160:163], v[200:203], v[28:31]
	v_mfma_f32_16x16x32_bf16 v[20:23], v[152:155], v[208:211], v[20:23]
	v_mfma_f32_16x16x32_bf16 v[12:15], v[160:163], v[208:211], v[12:15]
	v_mfma_f32_16x16x32_bf16 v[60:63], v[156:159], v[188:191], v[60:63]
	v_mfma_f32_16x16x32_bf16 v[56:59], v[164:167], v[188:191], v[56:59]
	v_mfma_f32_16x16x32_bf16 v[52:55], v[156:159], v[196:199], v[52:55]
	v_mfma_f32_16x16x32_bf16 v[44:47], v[164:167], v[196:199], v[44:47]
	s_mov_b32 m0, s44
	v_mfma_f32_16x16x32_bf16 v[36:39], v[156:159], v[204:207], v[36:39]
	global_load_lds_dwordx4 v[246:247], off
	v_mfma_f32_16x16x32_bf16 v[28:31], v[164:167], v[204:207], v[28:31]
	v_mfma_f32_16x16x32_bf16 v[20:23], v[156:159], v[212:215], v[20:23]
	v_mfma_f32_16x16x32_bf16 v[12:15], v[164:167], v[212:215], v[12:15]
	v_mfma_f32_16x16x32_bf16 v[48:51], v[168:171], v[184:187], v[48:51]
	v_mfma_f32_16x16x32_bf16 v[40:43], v[176:179], v[184:187], v[40:43]
	v_mfma_f32_16x16x32_bf16 v[32:35], v[168:171], v[192:195], v[32:35]
	v_mfma_f32_16x16x32_bf16 v[24:27], v[176:179], v[192:195], v[24:27]
	s_mov_b32 m0, s45
	v_mfma_f32_16x16x32_bf16 v[16:19], v[168:171], v[200:203], v[16:19]
	global_load_lds_dwordx4 v[144:145], off
	v_mfma_f32_16x16x32_bf16 v[8:11], v[176:179], v[200:203], v[8:11]
	v_mfma_f32_16x16x32_bf16 v[4:7], v[168:171], v[208:211], v[4:7]
	v_mfma_f32_16x16x32_bf16 v[0:3], v[176:179], v[208:211], v[0:3]
	v_mfma_f32_16x16x32_bf16 v[48:51], v[172:175], v[188:191], v[48:51]
	v_mfma_f32_16x16x32_bf16 v[40:43], v[180:183], v[188:191], v[40:43]
	v_mfma_f32_16x16x32_bf16 v[32:35], v[172:175], v[196:199], v[32:35]
	v_mfma_f32_16x16x32_bf16 v[24:27], v[180:183], v[196:199], v[24:27]
	v_mfma_f32_16x16x32_bf16 v[16:19], v[172:175], v[204:207], v[16:19]
	v_mfma_f32_16x16x32_bf16 v[8:11], v[180:183], v[204:207], v[8:11]
	v_mfma_f32_16x16x32_bf16 v[4:7], v[172:175], v[212:215], v[4:7]
	v_mfma_f32_16x16x32_bf16 v[0:3], v[180:183], v[212:215], v[0:3]
	s_barrier
	s_add_i32 s57, s57, 2
	s_add_u32 s36, s36, 0x100
	s_addc_u32 s37, s37, 0
	s_add_u32 s53, s53, 0x100
	s_addc_u32 s56, s56, 0
	s_cmp_gt_u32 s57, 13
	s_cbranch_scc0 .LBB0_993
	s_setprio 0
	s_and_b64 vcc, exec, s[8:9]
	s_cbranch_vccz .LBB0_996
	s_barrier
